# up-GEMM ACT stores and w_out-GEMM epilogue (in-place bf16 residual update) made lane-coalesced through a per-wave LDS stage
# speedup vs baseline: 1.1031x; 1.0032x over previous
.LBB0_744:
	v_readlane_b32 s78, v255, 4
	v_readlane_b32 s79, v255, 5
	v_mbcnt_lo_u32_b32 v1, -1, 0
	v_mbcnt_hi_u32_b32 v1, -1, v1
	v_and_b32_e32 v2, 15, v1
	v_sub_u32_e32 v250, v148, v2
	v_lshrrev_b32_e32 v251, 2, v1
	v_add_u32_e32 v250, v250, v251
	v_lshlrev_b32_e32 v250, 11, v250
	v_and_b32_e32 v150, 3, v1
	v_lshl_add_u32 v250, v150, 4, v250
	s_lshl_b32 s77, s10, 9
	s_lshl_b32 s80, s71, 6
	s_add_i32 s77, s77, s80
	v_add_u32_e32 v250, s77, v250
	s_lshr_b32 s77, s33, 6
	s_mulk_i32 s77, 0x500
	s_add_i32 s77, s77, 0x20400
	v_mul_u32_u24_e32 v251, 0x50, v251
	v_lshl_add_u32 v251, v150, 4, v251
	v_add_u32_e32 v251, s77, v251
	v_mul_u32_u24_e32 v252, 0x50, v2
	v_lshrrev_b32_e32 v1, 4, v1
	v_lshl_add_u32 v252, v1, 4, v252
	v_add_u32_e32 v252, s77, v252
	v_lshlrev_b32_e32 v253, 2, v148
	v_lshlrev_b32_e32 v254, 6, v148
	s_lshl_b32 s77, s10, 4
	s_lshl_b32 s80, s71, 2
	s_add_i32 s77, s77, s80
	v_add_u32_e32 v254, s77, v254
	v_add_u32_e32 v151, 0x2000, v254
	v_lshl_or_b32 v150, s10, 8, v164
	v_lshlrev_b32_e32 v150, 2, v150
	global_load_dwordx4 v[200:203], v150, s[78:79]
	global_load_dwordx4 v[204:207], v150, s[78:79] offset:16
	global_load_dwordx4 v[208:211], v150, s[78:79] offset:512
	global_load_dwordx4 v[212:215], v150, s[78:79] offset:528
	global_load_dword v216, v253, s[24:25]
	global_load_dword v217, v253, s[36:37]
	global_load_dword v218, v253, s[24:25] offset:64
	global_load_dword v219, v253, s[36:37] offset:64
	global_load_dword v220, v253, s[24:25] offset:128
	global_load_dword v221, v253, s[36:37] offset:128
	global_load_dword v222, v253, s[24:25] offset:192
	global_load_dword v223, v253, s[36:37] offset:192
	global_load_dword v224, v253, s[24:25] offset:512
	global_load_dword v225, v253, s[36:37] offset:512
	global_load_dword v226, v253, s[24:25] offset:576
	global_load_dword v227, v253, s[36:37] offset:576
	global_load_dword v228, v253, s[24:25] offset:640
	global_load_dword v229, v253, s[36:37] offset:640
	global_load_dword v230, v253, s[24:25] offset:704
	global_load_dword v231, v253, s[36:37] offset:704
	global_load_dwordx4 v[168:171], v250, s[12:13] nt
	global_load_dwordx4 v[172:175], v250, s[12:13] offset:256 nt
	v_add_u32_e32 v1, 0x8000, v250
	global_load_dwordx4 v[176:179], v1, s[12:13] nt
	v_add_u32_e32 v1, 0x8000, v250
	global_load_dwordx4 v[180:183], v1, s[12:13] offset:256 nt
	v_add_u32_e32 v1, 0x10000, v250
	global_load_dwordx4 v[184:187], v1, s[12:13] nt
	v_add_u32_e32 v1, 0x10000, v250
	global_load_dwordx4 v[188:191], v1, s[12:13] offset:256 nt
	v_add_u32_e32 v1, 0x18000, v250
	global_load_dwordx4 v[192:195], v1, s[12:13] nt
	v_add_u32_e32 v1, 0x18000, v250
	global_load_dwordx4 v[196:199], v1, s[12:13] offset:256 nt
	s_waitcnt vmcnt(24)
	v_rcp_f32_e32 v200, v200
	v_rcp_f32_e32 v201, v201
	v_rcp_f32_e32 v202, v202
	v_rcp_f32_e32 v203, v203
	v_rcp_f32_e32 v204, v204
	v_rcp_f32_e32 v205, v205
	v_rcp_f32_e32 v206, v206
	v_rcp_f32_e32 v207, v207
	v_rcp_f32_e32 v208, v208
	v_rcp_f32_e32 v209, v209
	v_rcp_f32_e32 v210, v210
	v_rcp_f32_e32 v211, v211
	v_rcp_f32_e32 v212, v212
	v_rcp_f32_e32 v213, v213
	v_rcp_f32_e32 v214, v214
	v_rcp_f32_e32 v215, v215
	s_waitcnt vmcnt(7)
	ds_write_b128 v251, v[168:171]
	ds_read_b128 v[168:171], v252
	s_waitcnt vmcnt(22)
	s_waitcnt lgkmcnt(0)
	v_lshlrev_b32_e32 v232, 16, v168
	v_and_b32_e32 v233, 0xffff0000, v168
	v_pk_mul_f32 v[232:233], v[232:233], v[200:201]
	v_pk_mul_f32 v[232:233], v[232:233], v[216:217] op_sel:[0,1]
	v_pk_fma_f32 v[128:129], v[128:129], v[216:217], v[232:233] op_sel_hi:[1,0,1]
	v_pk_mul_f32 v[236:237], v[128:129], v[128:129]
	v_lshlrev_b32_e32 v232, 16, v169
	v_and_b32_e32 v233, 0xffff0000, v169
	v_pk_mul_f32 v[232:233], v[232:233], v[202:203]
	v_pk_mul_f32 v[232:233], v[232:233], v[216:217] op_sel:[0,1]
	v_pk_fma_f32 v[130:131], v[130:131], v[216:217], v[232:233] op_sel_hi:[1,0,1]
	v_pk_fma_f32 v[236:237], v[130:131], v[130:131], v[236:237]
	v_cvt_pk_bf16_f32 v238, v128, v129
	v_cvt_pk_bf16_f32 v239, v130, v131
	v_lshlrev_b32_e32 v232, 16, v170
	v_and_b32_e32 v233, 0xffff0000, v170
	v_pk_mul_f32 v[232:233], v[232:233], v[204:205]
	v_pk_mul_f32 v[232:233], v[232:233], v[216:217] op_sel:[0,1]
	v_pk_fma_f32 v[124:125], v[124:125], v[216:217], v[232:233] op_sel_hi:[1,0,1]
	v_pk_fma_f32 v[236:237], v[124:125], v[124:125], v[236:237]
	v_lshlrev_b32_e32 v232, 16, v171
	v_and_b32_e32 v233, 0xffff0000, v171
	v_pk_mul_f32 v[232:233], v[232:233], v[206:207]
	v_pk_mul_f32 v[232:233], v[232:233], v[216:217] op_sel:[0,1]
	v_pk_fma_f32 v[126:127], v[126:127], v[216:217], v[232:233] op_sel_hi:[1,0,1]
	v_pk_fma_f32 v[236:237], v[126:127], v[126:127], v[236:237]
	v_cvt_pk_bf16_f32 v240, v124, v125
	v_cvt_pk_bf16_f32 v241, v126, v127
	ds_write_b128 v252, v[238:241]
	ds_read_b128 v[242:245], v251
	s_waitcnt lgkmcnt(0)
	global_store_dwordx4 v250, v[242:245], s[12:13]
	v_add_u32_e32 v1, 0x40000, v250
	global_load_dwordx4 v[168:171], v1, s[12:13] nt
	s_waitcnt vmcnt(8)
	ds_write_b128 v251, v[172:175]
	ds_read_b128 v[172:175], v252
	s_waitcnt lgkmcnt(0)
	v_lshlrev_b32_e32 v232, 16, v172
	v_and_b32_e32 v233, 0xffff0000, v172
	v_pk_mul_f32 v[232:233], v[232:233], v[208:209]
	v_pk_mul_f32 v[232:233], v[232:233], v[216:217] op_sel:[0,1]
	v_pk_fma_f32 v[120:121], v[120:121], v[216:217], v[232:233] op_sel_hi:[1,0,1]
	v_pk_fma_f32 v[236:237], v[120:121], v[120:121], v[236:237]
	v_lshlrev_b32_e32 v232, 16, v173
	v_and_b32_e32 v233, 0xffff0000, v173
	v_pk_mul_f32 v[232:233], v[232:233], v[210:211]
	v_pk_mul_f32 v[232:233], v[232:233], v[216:217] op_sel:[0,1]
	v_pk_fma_f32 v[122:123], v[122:123], v[216:217], v[232:233] op_sel_hi:[1,0,1]
	v_pk_fma_f32 v[236:237], v[122:123], v[122:123], v[236:237]
	v_cvt_pk_bf16_f32 v238, v120, v121
	v_cvt_pk_bf16_f32 v239, v122, v123
	v_lshlrev_b32_e32 v232, 16, v174
	v_and_b32_e32 v233, 0xffff0000, v174
	v_pk_mul_f32 v[232:233], v[232:233], v[212:213]
	v_pk_mul_f32 v[232:233], v[232:233], v[216:217] op_sel:[0,1]
	v_pk_fma_f32 v[116:117], v[116:117], v[216:217], v[232:233] op_sel_hi:[1,0,1]
	v_pk_fma_f32 v[236:237], v[116:117], v[116:117], v[236:237]
	v_lshlrev_b32_e32 v232, 16, v175
	v_and_b32_e32 v233, 0xffff0000, v175
	v_pk_mul_f32 v[232:233], v[232:233], v[214:215]
	v_pk_mul_f32 v[232:233], v[232:233], v[216:217] op_sel:[0,1]
	v_pk_fma_f32 v[118:119], v[118:119], v[216:217], v[232:233] op_sel_hi:[1,0,1]
	v_pk_fma_f32 v[236:237], v[118:119], v[118:119], v[236:237]
	v_cvt_pk_bf16_f32 v240, v116, v117
	v_cvt_pk_bf16_f32 v241, v118, v119
	ds_write_b128 v252, v[238:241]
	ds_read_b128 v[246:249], v251
	s_waitcnt lgkmcnt(0)
	global_store_dwordx4 v250, v[246:249], s[12:13] offset:256
	v_add_u32_e32 v1, 0x40000, v250
	global_load_dwordx4 v[172:175], v1, s[12:13] offset:256 nt
	v_add_f32_e32 v236, v236, v237
	ds_swizzle_b32 v152, v236 offset:0x401f
	s_waitcnt lgkmcnt(0)
	v_add_f32_e32 v236, v236, v152
	v_mov_b32_e32 v152, v236
	s_nop 1
	v_permlane32_swap_b32_e32 v236, v152
	v_add_f32_e32 v236, v236, v152
	s_mov_b64 exec, 0xffff
	global_store_dword v254, v236, s[38:39]
	s_mov_b64 exec, -1
	s_waitcnt vmcnt(10)
	ds_write_b128 v251, v[176:179]
	ds_read_b128 v[176:179], v252
	s_waitcnt vmcnt(25)
	s_waitcnt lgkmcnt(0)
	v_lshlrev_b32_e32 v232, 16, v176
	v_and_b32_e32 v233, 0xffff0000, v176
	v_pk_mul_f32 v[232:233], v[232:233], v[200:201]
	v_pk_mul_f32 v[232:233], v[232:233], v[218:219] op_sel:[0,1]
	v_pk_fma_f32 v[112:113], v[112:113], v[218:219], v[232:233] op_sel_hi:[1,0,1]
	v_pk_mul_f32 v[236:237], v[112:113], v[112:113]
	v_lshlrev_b32_e32 v232, 16, v177
	v_and_b32_e32 v233, 0xffff0000, v177
	v_pk_mul_f32 v[232:233], v[232:233], v[202:203]
	v_pk_mul_f32 v[232:233], v[232:233], v[218:219] op_sel:[0,1]
	v_pk_fma_f32 v[114:115], v[114:115], v[218:219], v[232:233] op_sel_hi:[1,0,1]
	v_pk_fma_f32 v[236:237], v[114:115], v[114:115], v[236:237]
	v_cvt_pk_bf16_f32 v238, v112, v113
	v_cvt_pk_bf16_f32 v239, v114, v115
	v_lshlrev_b32_e32 v232, 16, v178
	v_and_b32_e32 v233, 0xffff0000, v178
	v_pk_mul_f32 v[232:233], v[232:233], v[204:205]
	v_pk_mul_f32 v[232:233], v[232:233], v[218:219] op_sel:[0,1]
	v_pk_fma_f32 v[108:109], v[108:109], v[218:219], v[232:233] op_sel_hi:[1,0,1]
	v_pk_fma_f32 v[236:237], v[108:109], v[108:109], v[236:237]
	v_lshlrev_b32_e32 v232, 16, v179
	v_and_b32_e32 v233, 0xffff0000, v179
	v_pk_mul_f32 v[232:233], v[232:233], v[206:207]
	v_pk_mul_f32 v[232:233], v[232:233], v[218:219] op_sel:[0,1]
	v_pk_fma_f32 v[110:111], v[110:111], v[218:219], v[232:233] op_sel_hi:[1,0,1]
	v_pk_fma_f32 v[236:237], v[110:111], v[110:111], v[236:237]
	v_cvt_pk_bf16_f32 v240, v108, v109
	v_cvt_pk_bf16_f32 v241, v110, v111
	ds_write_b128 v252, v[238:241]
	ds_read_b128 v[242:245], v251
	v_add_u32_e32 v1, 0x8000, v250
	s_waitcnt lgkmcnt(0)
	global_store_dwordx4 v1, v[242:245], s[12:13]
	v_add_u32_e32 v1, 0x48000, v250
	global_load_dwordx4 v[176:179], v1, s[12:13] nt
	s_waitcnt vmcnt(11)
	ds_write_b128 v251, v[180:183]
	ds_read_b128 v[180:183], v252
	s_waitcnt lgkmcnt(0)
	v_lshlrev_b32_e32 v232, 16, v180
	v_and_b32_e32 v233, 0xffff0000, v180
	v_pk_mul_f32 v[232:233], v[232:233], v[208:209]
	v_pk_mul_f32 v[232:233], v[232:233], v[218:219] op_sel:[0,1]
	v_pk_fma_f32 v[104:105], v[104:105], v[218:219], v[232:233] op_sel_hi:[1,0,1]
	v_pk_fma_f32 v[236:237], v[104:105], v[104:105], v[236:237]
	v_lshlrev_b32_e32 v232, 16, v181
	v_and_b32_e32 v233, 0xffff0000, v181
	v_pk_mul_f32 v[232:233], v[232:233], v[210:211]
	v_pk_mul_f32 v[232:233], v[232:233], v[218:219] op_sel:[0,1]
	v_pk_fma_f32 v[106:107], v[106:107], v[218:219], v[232:233] op_sel_hi:[1,0,1]
	v_pk_fma_f32 v[236:237], v[106:107], v[106:107], v[236:237]
	v_cvt_pk_bf16_f32 v238, v104, v105
	v_cvt_pk_bf16_f32 v239, v106, v107
	v_lshlrev_b32_e32 v232, 16, v182
	v_and_b32_e32 v233, 0xffff0000, v182
	v_pk_mul_f32 v[232:233], v[232:233], v[212:213]
	v_pk_mul_f32 v[232:233], v[232:233], v[218:219] op_sel:[0,1]
	v_pk_fma_f32 v[100:101], v[100:101], v[218:219], v[232:233] op_sel_hi:[1,0,1]
	v_pk_fma_f32 v[236:237], v[100:101], v[100:101], v[236:237]
	v_lshlrev_b32_e32 v232, 16, v183
	v_and_b32_e32 v233, 0xffff0000, v183
	v_pk_mul_f32 v[232:233], v[232:233], v[214:215]
	v_pk_mul_f32 v[232:233], v[232:233], v[218:219] op_sel:[0,1]
	v_pk_fma_f32 v[102:103], v[102:103], v[218:219], v[232:233] op_sel_hi:[1,0,1]
	v_pk_fma_f32 v[236:237], v[102:103], v[102:103], v[236:237]
	v_cvt_pk_bf16_f32 v240, v100, v101
	v_cvt_pk_bf16_f32 v241, v102, v103
	ds_write_b128 v252, v[238:241]
	ds_read_b128 v[246:249], v251
	v_add_u32_e32 v1, 0x8000, v250
	s_waitcnt lgkmcnt(0)
	global_store_dwordx4 v1, v[246:249], s[12:13] offset:256
	v_add_u32_e32 v1, 0x48000, v250
	global_load_dwordx4 v[180:183], v1, s[12:13] offset:256 nt
	v_add_f32_e32 v236, v236, v237
	ds_swizzle_b32 v152, v236 offset:0x401f
	s_waitcnt lgkmcnt(0)
	v_add_f32_e32 v236, v236, v152
	v_mov_b32_e32 v152, v236
	s_nop 1
	v_permlane32_swap_b32_e32 v236, v152
	v_add_f32_e32 v236, v236, v152
	s_mov_b64 exec, 0xffff
	global_store_dword v254, v236, s[38:39] offset:1024
	s_mov_b64 exec, -1
	s_waitcnt vmcnt(13)
	ds_write_b128 v251, v[184:187]
	ds_read_b128 v[184:187], v252
	s_waitcnt vmcnt(28)
	s_waitcnt lgkmcnt(0)
	v_lshlrev_b32_e32 v232, 16, v184
	v_and_b32_e32 v233, 0xffff0000, v184
	v_pk_mul_f32 v[232:233], v[232:233], v[200:201]
	v_pk_mul_f32 v[232:233], v[232:233], v[220:221] op_sel:[0,1]
	v_pk_fma_f32 v[96:97], v[96:97], v[220:221], v[232:233] op_sel_hi:[1,0,1]
	v_pk_mul_f32 v[236:237], v[96:97], v[96:97]
	v_lshlrev_b32_e32 v232, 16, v185
	v_and_b32_e32 v233, 0xffff0000, v185
	v_pk_mul_f32 v[232:233], v[232:233], v[202:203]
	v_pk_mul_f32 v[232:233], v[232:233], v[220:221] op_sel:[0,1]
	v_pk_fma_f32 v[98:99], v[98:99], v[220:221], v[232:233] op_sel_hi:[1,0,1]
	v_pk_fma_f32 v[236:237], v[98:99], v[98:99], v[236:237]
	v_cvt_pk_bf16_f32 v238, v96, v97
	v_cvt_pk_bf16_f32 v239, v98, v99
	v_lshlrev_b32_e32 v232, 16, v186
	v_and_b32_e32 v233, 0xffff0000, v186
	v_pk_mul_f32 v[232:233], v[232:233], v[204:205]
	v_pk_mul_f32 v[232:233], v[232:233], v[220:221] op_sel:[0,1]
	v_pk_fma_f32 v[92:93], v[92:93], v[220:221], v[232:233] op_sel_hi:[1,0,1]
	v_pk_fma_f32 v[236:237], v[92:93], v[92:93], v[236:237]
	v_lshlrev_b32_e32 v232, 16, v187
	v_and_b32_e32 v233, 0xffff0000, v187
	v_pk_mul_f32 v[232:233], v[232:233], v[206:207]
	v_pk_mul_f32 v[232:233], v[232:233], v[220:221] op_sel:[0,1]
	v_pk_fma_f32 v[94:95], v[94:95], v[220:221], v[232:233] op_sel_hi:[1,0,1]
	v_pk_fma_f32 v[236:237], v[94:95], v[94:95], v[236:237]
	v_cvt_pk_bf16_f32 v240, v92, v93
	v_cvt_pk_bf16_f32 v241, v94, v95
	ds_write_b128 v252, v[238:241]
	ds_read_b128 v[242:245], v251
	v_add_u32_e32 v1, 0x10000, v250
	s_waitcnt lgkmcnt(0)
	global_store_dwordx4 v1, v[242:245], s[12:13]
	v_add_u32_e32 v1, 0x50000, v250
	global_load_dwordx4 v[184:187], v1, s[12:13] nt
	s_waitcnt vmcnt(14)
	ds_write_b128 v251, v[188:191]
	ds_read_b128 v[188:191], v252
	s_waitcnt lgkmcnt(0)
	v_lshlrev_b32_e32 v232, 16, v188
	v_and_b32_e32 v233, 0xffff0000, v188
	v_pk_mul_f32 v[232:233], v[232:233], v[208:209]
	v_pk_mul_f32 v[232:233], v[232:233], v[220:221] op_sel:[0,1]
	v_pk_fma_f32 v[88:89], v[88:89], v[220:221], v[232:233] op_sel_hi:[1,0,1]
	v_pk_fma_f32 v[236:237], v[88:89], v[88:89], v[236:237]
	v_lshlrev_b32_e32 v232, 16, v189
	v_and_b32_e32 v233, 0xffff0000, v189
	v_pk_mul_f32 v[232:233], v[232:233], v[210:211]
	v_pk_mul_f32 v[232:233], v[232:233], v[220:221] op_sel:[0,1]
	v_pk_fma_f32 v[90:91], v[90:91], v[220:221], v[232:233] op_sel_hi:[1,0,1]
	v_pk_fma_f32 v[236:237], v[90:91], v[90:91], v[236:237]
	v_cvt_pk_bf16_f32 v238, v88, v89
	v_cvt_pk_bf16_f32 v239, v90, v91
	v_lshlrev_b32_e32 v232, 16, v190
	v_and_b32_e32 v233, 0xffff0000, v190
	v_pk_mul_f32 v[232:233], v[232:233], v[212:213]
	v_pk_mul_f32 v[232:233], v[232:233], v[220:221] op_sel:[0,1]
	v_pk_fma_f32 v[84:85], v[84:85], v[220:221], v[232:233] op_sel_hi:[1,0,1]
	v_pk_fma_f32 v[236:237], v[84:85], v[84:85], v[236:237]
	v_lshlrev_b32_e32 v232, 16, v191
	v_and_b32_e32 v233, 0xffff0000, v191
	v_pk_mul_f32 v[232:233], v[232:233], v[214:215]
	v_pk_mul_f32 v[232:233], v[232:233], v[220:221] op_sel:[0,1]
	v_pk_fma_f32 v[86:87], v[86:87], v[220:221], v[232:233] op_sel_hi:[1,0,1]
	v_pk_fma_f32 v[236:237], v[86:87], v[86:87], v[236:237]
	v_cvt_pk_bf16_f32 v240, v84, v85
	v_cvt_pk_bf16_f32 v241, v86, v87
	ds_write_b128 v252, v[238:241]
	ds_read_b128 v[246:249], v251
	v_add_u32_e32 v1, 0x10000, v250
	s_waitcnt lgkmcnt(0)
	global_store_dwordx4 v1, v[246:249], s[12:13] offset:256
	v_add_u32_e32 v1, 0x50000, v250
	global_load_dwordx4 v[188:191], v1, s[12:13] offset:256 nt
	v_add_f32_e32 v236, v236, v237
	ds_swizzle_b32 v152, v236 offset:0x401f
	s_waitcnt lgkmcnt(0)
	v_add_f32_e32 v236, v236, v152
	v_mov_b32_e32 v152, v236
	s_nop 1
	v_permlane32_swap_b32_e32 v236, v152
	v_add_f32_e32 v236, v236, v152
	s_mov_b64 exec, 0xffff
	global_store_dword v254, v236, s[38:39] offset:2048
	s_mov_b64 exec, -1
	s_waitcnt vmcnt(16)
	ds_write_b128 v251, v[192:195]
	ds_read_b128 v[192:195], v252
	s_waitcnt vmcnt(31)
	s_waitcnt lgkmcnt(0)
	v_lshlrev_b32_e32 v232, 16, v192
	v_and_b32_e32 v233, 0xffff0000, v192
	v_pk_mul_f32 v[232:233], v[232:233], v[200:201]
	v_pk_mul_f32 v[232:233], v[232:233], v[222:223] op_sel:[0,1]
	v_pk_fma_f32 v[80:81], v[80:81], v[222:223], v[232:233] op_sel_hi:[1,0,1]
	v_pk_mul_f32 v[236:237], v[80:81], v[80:81]
	v_lshlrev_b32_e32 v232, 16, v193
	v_and_b32_e32 v233, 0xffff0000, v193
	v_pk_mul_f32 v[232:233], v[232:233], v[202:203]
	v_pk_mul_f32 v[232:233], v[232:233], v[222:223] op_sel:[0,1]
	v_pk_fma_f32 v[82:83], v[82:83], v[222:223], v[232:233] op_sel_hi:[1,0,1]
	v_pk_fma_f32 v[236:237], v[82:83], v[82:83], v[236:237]
	v_cvt_pk_bf16_f32 v238, v80, v81
	v_cvt_pk_bf16_f32 v239, v82, v83
	v_lshlrev_b32_e32 v232, 16, v194
	v_and_b32_e32 v233, 0xffff0000, v194
	v_pk_mul_f32 v[232:233], v[232:233], v[204:205]
	v_pk_mul_f32 v[232:233], v[232:233], v[222:223] op_sel:[0,1]
	v_pk_fma_f32 v[76:77], v[76:77], v[222:223], v[232:233] op_sel_hi:[1,0,1]
	v_pk_fma_f32 v[236:237], v[76:77], v[76:77], v[236:237]
	v_lshlrev_b32_e32 v232, 16, v195
	v_and_b32_e32 v233, 0xffff0000, v195
	v_pk_mul_f32 v[232:233], v[232:233], v[206:207]
	v_pk_mul_f32 v[232:233], v[232:233], v[222:223] op_sel:[0,1]
	v_pk_fma_f32 v[78:79], v[78:79], v[222:223], v[232:233] op_sel_hi:[1,0,1]
	v_pk_fma_f32 v[236:237], v[78:79], v[78:79], v[236:237]
	v_cvt_pk_bf16_f32 v240, v76, v77
	v_cvt_pk_bf16_f32 v241, v78, v79
	ds_write_b128 v252, v[238:241]
	ds_read_b128 v[242:245], v251
	v_add_u32_e32 v1, 0x18000, v250
	s_waitcnt lgkmcnt(0)
	global_store_dwordx4 v1, v[242:245], s[12:13]
	v_add_u32_e32 v1, 0x58000, v250
	global_load_dwordx4 v[192:195], v1, s[12:13] nt
	s_waitcnt vmcnt(17)
	ds_write_b128 v251, v[196:199]
	ds_read_b128 v[196:199], v252
	s_waitcnt lgkmcnt(0)
	v_lshlrev_b32_e32 v232, 16, v196
	v_and_b32_e32 v233, 0xffff0000, v196
	v_pk_mul_f32 v[232:233], v[232:233], v[208:209]
	v_pk_mul_f32 v[232:233], v[232:233], v[222:223] op_sel:[0,1]
	v_pk_fma_f32 v[72:73], v[72:73], v[222:223], v[232:233] op_sel_hi:[1,0,1]
	v_pk_fma_f32 v[236:237], v[72:73], v[72:73], v[236:237]
	v_lshlrev_b32_e32 v232, 16, v197
	v_and_b32_e32 v233, 0xffff0000, v197
	v_pk_mul_f32 v[232:233], v[232:233], v[210:211]
	v_pk_mul_f32 v[232:233], v[232:233], v[222:223] op_sel:[0,1]
	v_pk_fma_f32 v[74:75], v[74:75], v[222:223], v[232:233] op_sel_hi:[1,0,1]
	v_pk_fma_f32 v[236:237], v[74:75], v[74:75], v[236:237]
	v_cvt_pk_bf16_f32 v238, v72, v73
	v_cvt_pk_bf16_f32 v239, v74, v75
	v_lshlrev_b32_e32 v232, 16, v198
	v_and_b32_e32 v233, 0xffff0000, v198
	v_pk_mul_f32 v[232:233], v[232:233], v[212:213]
	v_pk_mul_f32 v[232:233], v[232:233], v[222:223] op_sel:[0,1]
	v_pk_fma_f32 v[68:69], v[68:69], v[222:223], v[232:233] op_sel_hi:[1,0,1]
	v_pk_fma_f32 v[236:237], v[68:69], v[68:69], v[236:237]
	v_lshlrev_b32_e32 v232, 16, v199
	v_and_b32_e32 v233, 0xffff0000, v199
	v_pk_mul_f32 v[232:233], v[232:233], v[214:215]
	v_pk_mul_f32 v[232:233], v[232:233], v[222:223] op_sel:[0,1]
	v_pk_fma_f32 v[70:71], v[70:71], v[222:223], v[232:233] op_sel_hi:[1,0,1]
	v_pk_fma_f32 v[236:237], v[70:71], v[70:71], v[236:237]
	v_cvt_pk_bf16_f32 v240, v68, v69
	v_cvt_pk_bf16_f32 v241, v70, v71
	ds_write_b128 v252, v[238:241]
	ds_read_b128 v[246:249], v251
	v_add_u32_e32 v1, 0x18000, v250
	s_waitcnt lgkmcnt(0)
	global_store_dwordx4 v1, v[246:249], s[12:13] offset:256
	v_add_u32_e32 v1, 0x58000, v250
	global_load_dwordx4 v[196:199], v1, s[12:13] offset:256 nt
	v_add_f32_e32 v236, v236, v237
	ds_swizzle_b32 v152, v236 offset:0x401f
	s_waitcnt lgkmcnt(0)
	v_add_f32_e32 v236, v236, v152
	v_mov_b32_e32 v152, v236
	s_nop 1
	v_permlane32_swap_b32_e32 v236, v152
	v_add_f32_e32 v236, v236, v152
	s_mov_b64 exec, 0xffff
	global_store_dword v254, v236, s[38:39] offset:3072
	s_mov_b64 exec, -1
	s_waitcnt vmcnt(18)
	ds_write_b128 v251, v[168:171]
	ds_read_b128 v[168:171], v252
	s_waitcnt vmcnt(34)
	s_waitcnt lgkmcnt(0)
	v_lshlrev_b32_e32 v232, 16, v168
	v_and_b32_e32 v233, 0xffff0000, v168
	v_pk_mul_f32 v[232:233], v[232:233], v[200:201]
	v_pk_mul_f32 v[232:233], v[232:233], v[224:225] op_sel:[0,1]
	v_pk_fma_f32 v[64:65], v[64:65], v[224:225], v[232:233] op_sel_hi:[1,0,1]
	v_pk_mul_f32 v[236:237], v[64:65], v[64:65]
	v_lshlrev_b32_e32 v232, 16, v169
	v_and_b32_e32 v233, 0xffff0000, v169
	v_pk_mul_f32 v[232:233], v[232:233], v[202:203]
	v_pk_mul_f32 v[232:233], v[232:233], v[224:225] op_sel:[0,1]
	v_pk_fma_f32 v[66:67], v[66:67], v[224:225], v[232:233] op_sel_hi:[1,0,1]
	v_pk_fma_f32 v[236:237], v[66:67], v[66:67], v[236:237]
	v_cvt_pk_bf16_f32 v238, v64, v65
	v_cvt_pk_bf16_f32 v239, v66, v67
	v_lshlrev_b32_e32 v232, 16, v170
	v_and_b32_e32 v233, 0xffff0000, v170
	v_pk_mul_f32 v[232:233], v[232:233], v[204:205]
	v_pk_mul_f32 v[232:233], v[232:233], v[224:225] op_sel:[0,1]
	v_pk_fma_f32 v[60:61], v[60:61], v[224:225], v[232:233] op_sel_hi:[1,0,1]
	v_pk_fma_f32 v[236:237], v[60:61], v[60:61], v[236:237]
	v_lshlrev_b32_e32 v232, 16, v171
	v_and_b32_e32 v233, 0xffff0000, v171
	v_pk_mul_f32 v[232:233], v[232:233], v[206:207]
	v_pk_mul_f32 v[232:233], v[232:233], v[224:225] op_sel:[0,1]
	v_pk_fma_f32 v[62:63], v[62:63], v[224:225], v[232:233] op_sel_hi:[1,0,1]
	v_pk_fma_f32 v[236:237], v[62:63], v[62:63], v[236:237]
	v_cvt_pk_bf16_f32 v240, v60, v61
	v_cvt_pk_bf16_f32 v241, v62, v63
	ds_write_b128 v252, v[238:241]
	ds_read_b128 v[242:245], v251
	v_add_u32_e32 v1, 0x40000, v250
	s_waitcnt lgkmcnt(0)
	global_store_dwordx4 v1, v[242:245], s[12:13]
	s_waitcnt vmcnt(17)
	ds_write_b128 v251, v[172:175]
	ds_read_b128 v[172:175], v252
	s_waitcnt lgkmcnt(0)
	v_lshlrev_b32_e32 v232, 16, v172
	v_and_b32_e32 v233, 0xffff0000, v172
	v_pk_mul_f32 v[232:233], v[232:233], v[208:209]
	v_pk_mul_f32 v[232:233], v[232:233], v[224:225] op_sel:[0,1]
	v_pk_fma_f32 v[56:57], v[56:57], v[224:225], v[232:233] op_sel_hi:[1,0,1]
	v_pk_fma_f32 v[236:237], v[56:57], v[56:57], v[236:237]
	v_lshlrev_b32_e32 v232, 16, v173
	v_and_b32_e32 v233, 0xffff0000, v173
	v_pk_mul_f32 v[232:233], v[232:233], v[210:211]
	v_pk_mul_f32 v[232:233], v[232:233], v[224:225] op_sel:[0,1]
	v_pk_fma_f32 v[58:59], v[58:59], v[224:225], v[232:233] op_sel_hi:[1,0,1]
	v_pk_fma_f32 v[236:237], v[58:59], v[58:59], v[236:237]
	v_cvt_pk_bf16_f32 v238, v56, v57
	v_cvt_pk_bf16_f32 v239, v58, v59
	v_lshlrev_b32_e32 v232, 16, v174
	v_and_b32_e32 v233, 0xffff0000, v174
	v_pk_mul_f32 v[232:233], v[232:233], v[212:213]
	v_pk_mul_f32 v[232:233], v[232:233], v[224:225] op_sel:[0,1]
	v_pk_fma_f32 v[52:53], v[52:53], v[224:225], v[232:233] op_sel_hi:[1,0,1]
	v_pk_fma_f32 v[236:237], v[52:53], v[52:53], v[236:237]
	v_lshlrev_b32_e32 v232, 16, v175
	v_and_b32_e32 v233, 0xffff0000, v175
	v_pk_mul_f32 v[232:233], v[232:233], v[214:215]
	v_pk_mul_f32 v[232:233], v[232:233], v[224:225] op_sel:[0,1]
	v_pk_fma_f32 v[54:55], v[54:55], v[224:225], v[232:233] op_sel_hi:[1,0,1]
	v_pk_fma_f32 v[236:237], v[54:55], v[54:55], v[236:237]
	v_cvt_pk_bf16_f32 v240, v52, v53
	v_cvt_pk_bf16_f32 v241, v54, v55
	ds_write_b128 v252, v[238:241]
	ds_read_b128 v[246:249], v251
	v_add_u32_e32 v1, 0x40000, v250
	s_waitcnt lgkmcnt(0)
	global_store_dwordx4 v1, v[246:249], s[12:13] offset:256
	v_add_f32_e32 v236, v236, v237
	ds_swizzle_b32 v152, v236 offset:0x401f
	s_waitcnt lgkmcnt(0)
	v_add_f32_e32 v236, v236, v152
	v_mov_b32_e32 v152, v236
	s_nop 1
	v_permlane32_swap_b32_e32 v236, v152
	v_add_f32_e32 v236, v236, v152
	s_mov_b64 exec, 0xffff
	global_store_dword v151, v236, s[38:39]
	s_mov_b64 exec, -1
	s_waitcnt vmcnt(16)
	ds_write_b128 v251, v[176:179]
	ds_read_b128 v[176:179], v252
	s_waitcnt vmcnt(35)
	s_waitcnt lgkmcnt(0)
	v_lshlrev_b32_e32 v232, 16, v176
	v_and_b32_e32 v233, 0xffff0000, v176
	v_pk_mul_f32 v[232:233], v[232:233], v[200:201]
	v_pk_mul_f32 v[232:233], v[232:233], v[226:227] op_sel:[0,1]
	v_pk_fma_f32 v[48:49], v[48:49], v[226:227], v[232:233] op_sel_hi:[1,0,1]
	v_pk_mul_f32 v[236:237], v[48:49], v[48:49]
	v_lshlrev_b32_e32 v232, 16, v177
	v_and_b32_e32 v233, 0xffff0000, v177
	v_pk_mul_f32 v[232:233], v[232:233], v[202:203]
	v_pk_mul_f32 v[232:233], v[232:233], v[226:227] op_sel:[0,1]
	v_pk_fma_f32 v[50:51], v[50:51], v[226:227], v[232:233] op_sel_hi:[1,0,1]
	v_pk_fma_f32 v[236:237], v[50:51], v[50:51], v[236:237]
	v_cvt_pk_bf16_f32 v238, v48, v49
	v_cvt_pk_bf16_f32 v239, v50, v51
	v_lshlrev_b32_e32 v232, 16, v178
	v_and_b32_e32 v233, 0xffff0000, v178
	v_pk_mul_f32 v[232:233], v[232:233], v[204:205]
	v_pk_mul_f32 v[232:233], v[232:233], v[226:227] op_sel:[0,1]
	v_pk_fma_f32 v[44:45], v[44:45], v[226:227], v[232:233] op_sel_hi:[1,0,1]
	v_pk_fma_f32 v[236:237], v[44:45], v[44:45], v[236:237]
	v_lshlrev_b32_e32 v232, 16, v179
	v_and_b32_e32 v233, 0xffff0000, v179
	v_pk_mul_f32 v[232:233], v[232:233], v[206:207]
	v_pk_mul_f32 v[232:233], v[232:233], v[226:227] op_sel:[0,1]
	v_pk_fma_f32 v[46:47], v[46:47], v[226:227], v[232:233] op_sel_hi:[1,0,1]
	v_pk_fma_f32 v[236:237], v[46:47], v[46:47], v[236:237]
	v_cvt_pk_bf16_f32 v240, v44, v45
	v_cvt_pk_bf16_f32 v241, v46, v47
	ds_write_b128 v252, v[238:241]
	ds_read_b128 v[242:245], v251
	v_add_u32_e32 v1, 0x48000, v250
	s_waitcnt lgkmcnt(0)
	global_store_dwordx4 v1, v[242:245], s[12:13]
	s_waitcnt vmcnt(15)
	ds_write_b128 v251, v[180:183]
	ds_read_b128 v[180:183], v252
	s_waitcnt lgkmcnt(0)
	v_lshlrev_b32_e32 v232, 16, v180
	v_and_b32_e32 v233, 0xffff0000, v180
	v_pk_mul_f32 v[232:233], v[232:233], v[208:209]
	v_pk_mul_f32 v[232:233], v[232:233], v[226:227] op_sel:[0,1]
	v_pk_fma_f32 v[40:41], v[40:41], v[226:227], v[232:233] op_sel_hi:[1,0,1]
	v_pk_fma_f32 v[236:237], v[40:41], v[40:41], v[236:237]
	v_lshlrev_b32_e32 v232, 16, v181
	v_and_b32_e32 v233, 0xffff0000, v181
	v_pk_mul_f32 v[232:233], v[232:233], v[210:211]
	v_pk_mul_f32 v[232:233], v[232:233], v[226:227] op_sel:[0,1]
	v_pk_fma_f32 v[42:43], v[42:43], v[226:227], v[232:233] op_sel_hi:[1,0,1]
	v_pk_fma_f32 v[236:237], v[42:43], v[42:43], v[236:237]
	v_cvt_pk_bf16_f32 v238, v40, v41
	v_cvt_pk_bf16_f32 v239, v42, v43
	v_lshlrev_b32_e32 v232, 16, v182
	v_and_b32_e32 v233, 0xffff0000, v182
	v_pk_mul_f32 v[232:233], v[232:233], v[212:213]
	v_pk_mul_f32 v[232:233], v[232:233], v[226:227] op_sel:[0,1]
	v_pk_fma_f32 v[36:37], v[36:37], v[226:227], v[232:233] op_sel_hi:[1,0,1]
	v_pk_fma_f32 v[236:237], v[36:37], v[36:37], v[236:237]
	v_lshlrev_b32_e32 v232, 16, v183
	v_and_b32_e32 v233, 0xffff0000, v183
	v_pk_mul_f32 v[232:233], v[232:233], v[214:215]
	v_pk_mul_f32 v[232:233], v[232:233], v[226:227] op_sel:[0,1]
	v_pk_fma_f32 v[38:39], v[38:39], v[226:227], v[232:233] op_sel_hi:[1,0,1]
	v_pk_fma_f32 v[236:237], v[38:39], v[38:39], v[236:237]
	v_cvt_pk_bf16_f32 v240, v36, v37
	v_cvt_pk_bf16_f32 v241, v38, v39
	ds_write_b128 v252, v[238:241]
	ds_read_b128 v[246:249], v251
	v_add_u32_e32 v1, 0x48000, v250
	s_waitcnt lgkmcnt(0)
	global_store_dwordx4 v1, v[246:249], s[12:13] offset:256
	v_add_f32_e32 v236, v236, v237
	ds_swizzle_b32 v152, v236 offset:0x401f
	s_waitcnt lgkmcnt(0)
	v_add_f32_e32 v236, v236, v152
	v_mov_b32_e32 v152, v236
	s_nop 1
	v_permlane32_swap_b32_e32 v236, v152
	v_add_f32_e32 v236, v236, v152
	s_mov_b64 exec, 0xffff
	global_store_dword v151, v236, s[38:39] offset:1024
	s_mov_b64 exec, -1
	s_waitcnt vmcnt(14)
	ds_write_b128 v251, v[184:187]
	ds_read_b128 v[184:187], v252
	s_waitcnt vmcnt(36)
	s_waitcnt lgkmcnt(0)
	v_lshlrev_b32_e32 v232, 16, v184
	v_and_b32_e32 v233, 0xffff0000, v184
	v_pk_mul_f32 v[232:233], v[232:233], v[200:201]
	v_pk_mul_f32 v[232:233], v[232:233], v[228:229] op_sel:[0,1]
	v_pk_fma_f32 v[32:33], v[32:33], v[228:229], v[232:233] op_sel_hi:[1,0,1]
	v_pk_mul_f32 v[236:237], v[32:33], v[32:33]
	v_lshlrev_b32_e32 v232, 16, v185
	v_and_b32_e32 v233, 0xffff0000, v185
	v_pk_mul_f32 v[232:233], v[232:233], v[202:203]
	v_pk_mul_f32 v[232:233], v[232:233], v[228:229] op_sel:[0,1]
	v_pk_fma_f32 v[34:35], v[34:35], v[228:229], v[232:233] op_sel_hi:[1,0,1]
	v_pk_fma_f32 v[236:237], v[34:35], v[34:35], v[236:237]
	v_cvt_pk_bf16_f32 v238, v32, v33
	v_cvt_pk_bf16_f32 v239, v34, v35
	v_lshlrev_b32_e32 v232, 16, v186
	v_and_b32_e32 v233, 0xffff0000, v186
	v_pk_mul_f32 v[232:233], v[232:233], v[204:205]
	v_pk_mul_f32 v[232:233], v[232:233], v[228:229] op_sel:[0,1]
	v_pk_fma_f32 v[28:29], v[28:29], v[228:229], v[232:233] op_sel_hi:[1,0,1]
	v_pk_fma_f32 v[236:237], v[28:29], v[28:29], v[236:237]
	v_lshlrev_b32_e32 v232, 16, v187
	v_and_b32_e32 v233, 0xffff0000, v187
	v_pk_mul_f32 v[232:233], v[232:233], v[206:207]
	v_pk_mul_f32 v[232:233], v[232:233], v[228:229] op_sel:[0,1]
	v_pk_fma_f32 v[30:31], v[30:31], v[228:229], v[232:233] op_sel_hi:[1,0,1]
	v_pk_fma_f32 v[236:237], v[30:31], v[30:31], v[236:237]
	v_cvt_pk_bf16_f32 v240, v28, v29
	v_cvt_pk_bf16_f32 v241, v30, v31
	ds_write_b128 v252, v[238:241]
	ds_read_b128 v[242:245], v251
	v_add_u32_e32 v1, 0x50000, v250
	s_waitcnt lgkmcnt(0)
	global_store_dwordx4 v1, v[242:245], s[12:13]
	s_waitcnt vmcnt(13)
	ds_write_b128 v251, v[188:191]
	ds_read_b128 v[188:191], v252
	s_waitcnt lgkmcnt(0)
	v_lshlrev_b32_e32 v232, 16, v188
	v_and_b32_e32 v233, 0xffff0000, v188
	v_pk_mul_f32 v[232:233], v[232:233], v[208:209]
	v_pk_mul_f32 v[232:233], v[232:233], v[228:229] op_sel:[0,1]
	v_pk_fma_f32 v[24:25], v[24:25], v[228:229], v[232:233] op_sel_hi:[1,0,1]
	v_pk_fma_f32 v[236:237], v[24:25], v[24:25], v[236:237]
	v_lshlrev_b32_e32 v232, 16, v189
	v_and_b32_e32 v233, 0xffff0000, v189
	v_pk_mul_f32 v[232:233], v[232:233], v[210:211]
	v_pk_mul_f32 v[232:233], v[232:233], v[228:229] op_sel:[0,1]
	v_pk_fma_f32 v[26:27], v[26:27], v[228:229], v[232:233] op_sel_hi:[1,0,1]
	v_pk_fma_f32 v[236:237], v[26:27], v[26:27], v[236:237]
	v_cvt_pk_bf16_f32 v238, v24, v25
	v_cvt_pk_bf16_f32 v239, v26, v27
	v_lshlrev_b32_e32 v232, 16, v190
	v_and_b32_e32 v233, 0xffff0000, v190
	v_pk_mul_f32 v[232:233], v[232:233], v[212:213]
	v_pk_mul_f32 v[232:233], v[232:233], v[228:229] op_sel:[0,1]
	v_pk_fma_f32 v[20:21], v[20:21], v[228:229], v[232:233] op_sel_hi:[1,0,1]
	v_pk_fma_f32 v[236:237], v[20:21], v[20:21], v[236:237]
	v_lshlrev_b32_e32 v232, 16, v191
	v_and_b32_e32 v233, 0xffff0000, v191
	v_pk_mul_f32 v[232:233], v[232:233], v[214:215]
	v_pk_mul_f32 v[232:233], v[232:233], v[228:229] op_sel:[0,1]
	v_pk_fma_f32 v[22:23], v[22:23], v[228:229], v[232:233] op_sel_hi:[1,0,1]
	v_pk_fma_f32 v[236:237], v[22:23], v[22:23], v[236:237]
	v_cvt_pk_bf16_f32 v240, v20, v21
	v_cvt_pk_bf16_f32 v241, v22, v23
	ds_write_b128 v252, v[238:241]
	ds_read_b128 v[246:249], v251
	v_add_u32_e32 v1, 0x50000, v250
	s_waitcnt lgkmcnt(0)
	global_store_dwordx4 v1, v[246:249], s[12:13] offset:256
	v_add_f32_e32 v236, v236, v237
	ds_swizzle_b32 v152, v236 offset:0x401f
	s_waitcnt lgkmcnt(0)
	v_add_f32_e32 v236, v236, v152
	v_mov_b32_e32 v152, v236
	s_nop 1
	v_permlane32_swap_b32_e32 v236, v152
	v_add_f32_e32 v236, v236, v152
	s_mov_b64 exec, 0xffff
	global_store_dword v151, v236, s[38:39] offset:2048
	s_mov_b64 exec, -1
	s_waitcnt vmcnt(12)
	ds_write_b128 v251, v[192:195]
	ds_read_b128 v[192:195], v252
	s_waitcnt vmcnt(37)
	s_waitcnt lgkmcnt(0)
	v_lshlrev_b32_e32 v232, 16, v192
	v_and_b32_e32 v233, 0xffff0000, v192
	v_pk_mul_f32 v[232:233], v[232:233], v[200:201]
	v_pk_mul_f32 v[232:233], v[232:233], v[230:231] op_sel:[0,1]
	v_pk_fma_f32 v[16:17], v[16:17], v[230:231], v[232:233] op_sel_hi:[1,0,1]
	v_pk_mul_f32 v[236:237], v[16:17], v[16:17]
	v_lshlrev_b32_e32 v232, 16, v193
	v_and_b32_e32 v233, 0xffff0000, v193
	v_pk_mul_f32 v[232:233], v[232:233], v[202:203]
	v_pk_mul_f32 v[232:233], v[232:233], v[230:231] op_sel:[0,1]
	v_pk_fma_f32 v[18:19], v[18:19], v[230:231], v[232:233] op_sel_hi:[1,0,1]
	v_pk_fma_f32 v[236:237], v[18:19], v[18:19], v[236:237]
	v_cvt_pk_bf16_f32 v238, v16, v17
	v_cvt_pk_bf16_f32 v239, v18, v19
	v_lshlrev_b32_e32 v232, 16, v194
	v_and_b32_e32 v233, 0xffff0000, v194
	v_pk_mul_f32 v[232:233], v[232:233], v[204:205]
	v_pk_mul_f32 v[232:233], v[232:233], v[230:231] op_sel:[0,1]
	v_pk_fma_f32 v[12:13], v[12:13], v[230:231], v[232:233] op_sel_hi:[1,0,1]
	v_pk_fma_f32 v[236:237], v[12:13], v[12:13], v[236:237]
	v_lshlrev_b32_e32 v232, 16, v195
	v_and_b32_e32 v233, 0xffff0000, v195
	v_pk_mul_f32 v[232:233], v[232:233], v[206:207]
	v_pk_mul_f32 v[232:233], v[232:233], v[230:231] op_sel:[0,1]
	v_pk_fma_f32 v[14:15], v[14:15], v[230:231], v[232:233] op_sel_hi:[1,0,1]
	v_pk_fma_f32 v[236:237], v[14:15], v[14:15], v[236:237]
	v_cvt_pk_bf16_f32 v240, v12, v13
	v_cvt_pk_bf16_f32 v241, v14, v15
	ds_write_b128 v252, v[238:241]
	ds_read_b128 v[242:245], v251
	v_add_u32_e32 v1, 0x58000, v250
	s_waitcnt lgkmcnt(0)
	global_store_dwordx4 v1, v[242:245], s[12:13]
	s_waitcnt vmcnt(11)
	ds_write_b128 v251, v[196:199]
	ds_read_b128 v[196:199], v252
	s_waitcnt lgkmcnt(0)
	v_lshlrev_b32_e32 v232, 16, v196
	v_and_b32_e32 v233, 0xffff0000, v196
	v_pk_mul_f32 v[232:233], v[232:233], v[208:209]
	v_pk_mul_f32 v[232:233], v[232:233], v[230:231] op_sel:[0,1]
	v_pk_fma_f32 v[8:9], v[8:9], v[230:231], v[232:233] op_sel_hi:[1,0,1]
	v_pk_fma_f32 v[236:237], v[8:9], v[8:9], v[236:237]
	v_lshlrev_b32_e32 v232, 16, v197
	v_and_b32_e32 v233, 0xffff0000, v197
	v_pk_mul_f32 v[232:233], v[232:233], v[210:211]
	v_pk_mul_f32 v[232:233], v[232:233], v[230:231] op_sel:[0,1]
	v_pk_fma_f32 v[10:11], v[10:11], v[230:231], v[232:233] op_sel_hi:[1,0,1]
	v_pk_fma_f32 v[236:237], v[10:11], v[10:11], v[236:237]
	v_cvt_pk_bf16_f32 v238, v8, v9
	v_cvt_pk_bf16_f32 v239, v10, v11
	v_lshlrev_b32_e32 v232, 16, v198
	v_and_b32_e32 v233, 0xffff0000, v198
	v_pk_mul_f32 v[232:233], v[232:233], v[212:213]
	v_pk_mul_f32 v[232:233], v[232:233], v[230:231] op_sel:[0,1]
	v_pk_fma_f32 v[4:5], v[4:5], v[230:231], v[232:233] op_sel_hi:[1,0,1]
	v_pk_fma_f32 v[236:237], v[4:5], v[4:5], v[236:237]
	v_lshlrev_b32_e32 v232, 16, v199
	v_and_b32_e32 v233, 0xffff0000, v199
	v_pk_mul_f32 v[232:233], v[232:233], v[214:215]
	v_pk_mul_f32 v[232:233], v[232:233], v[230:231] op_sel:[0,1]
	v_pk_fma_f32 v[6:7], v[6:7], v[230:231], v[232:233] op_sel_hi:[1,0,1]
	v_pk_fma_f32 v[236:237], v[6:7], v[6:7], v[236:237]
	v_cvt_pk_bf16_f32 v240, v4, v5
	v_cvt_pk_bf16_f32 v241, v6, v7
	ds_write_b128 v252, v[238:241]
	ds_read_b128 v[246:249], v251
	v_add_u32_e32 v1, 0x58000, v250
	s_waitcnt lgkmcnt(0)
	global_store_dwordx4 v1, v[246:249], s[12:13] offset:256
	v_add_f32_e32 v236, v236, v237
	ds_swizzle_b32 v152, v236 offset:0x401f
	s_waitcnt lgkmcnt(0)
	v_add_f32_e32 v236, v236, v152
	v_mov_b32_e32 v152, v236
	s_nop 1
	v_permlane32_swap_b32_e32 v236, v152
	v_add_f32_e32 v236, v236, v152
	s_mov_b64 exec, 0xffff
	global_store_dword v151, v236, s[38:39] offset:3072
	s_mov_b64 exec, -1

.LBB0_925:
	s_or_b64 exec, exec, s[58:59]
	v_pk_mul_f32 v[46:47], v[46:47], v[68:69] op_sel:[0,1]
	v_pk_mul_f32 v[252:253], v[32:33], v[68:69] op_sel:[0,1]
	s_waitcnt vmcnt(0)
	v_pk_mul_f32 v[32:33], v[204:205], v[108:109]
	v_mov_b32_e32 v232, v67
	v_pk_fma_f32 v[32:33], v[46:47], v[104:105], v[32:33]
	v_pk_mul_f32 v[244:245], v[54:55], v[68:69] op_sel_hi:[1,0]
	v_pk_fma_f32 v[32:33], v[212:213], v[116:117], v[32:33]
	v_pk_mul_f32 v[54:55], v[48:49], v[66:67] op_sel_hi:[1,0]
	v_pk_add_f32 v[32:33], v[32:33], v[112:113]
	v_pk_mul_f32 v[48:49], v[42:43], v[232:233] op_sel_hi:[1,0]
	v_mul_f32_e32 v42, 0xbfb8aa3b, v32
	v_mul_f32_e32 v43, 0xbfb8aa3b, v33
	v_exp_f32_e32 v42, v42
	v_exp_f32_e32 v43, v43
	v_pk_mul_f32 v[44:45], v[44:45], v[68:69] op_sel:[0,1]
	v_pk_mul_f32 v[250:251], v[34:35], v[68:69] op_sel:[0,1]
	v_pk_mul_f32 v[34:35], v[206:207], v[106:107]
	v_add_f32_e32 v42, 1.0, v42
	v_pk_fma_f32 v[34:35], v[44:45], v[102:103], v[34:35]
	v_add_f32_e32 v43, 1.0, v43
	v_pk_fma_f32 v[34:35], v[214:215], v[114:115], v[34:35]
	v_pk_mul_f32 v[242:243], v[52:53], v[68:69] op_sel_hi:[1,0]
	v_pk_add_f32 v[34:35], v[34:35], v[110:111]
	v_pk_mul_f32 v[52:53], v[50:51], v[66:67] op_sel_hi:[1,0]
	v_pk_mul_f32 v[50:51], v[40:41], v[232:233] op_sel_hi:[1,0]
	v_mul_f32_e32 v40, 0xbfb8aa3b, v34
	v_mul_f32_e32 v41, 0xbfb8aa3b, v35
	v_rcp_f32_e32 v42, v42
	v_rcp_f32_e32 v43, v43
	v_pk_mul_f32 v[248:249], v[36:37], v[68:69] op_sel_hi:[1,0]
	v_pk_mul_f32 v[36:37], v[202:203], v[124:125]
	v_exp_f32_e32 v40, v40
	v_exp_f32_e32 v41, v41
	v_pk_fma_f32 v[36:37], v[250:251], v[120:121], v[36:37]
	v_pk_mul_f32 v[32:33], v[32:33], v[42:43]
	v_pk_fma_f32 v[36:37], v[208:209], v[132:133], v[36:37]
	v_add_f32_e32 v40, 1.0, v40
	v_pk_add_f32 v[36:37], v[36:37], v[128:129]
	v_add_f32_e32 v41, 1.0, v41
	v_pk_mul_f32 v[32:33], v[32:33], v[36:37]
	v_pk_mul_f32 v[36:37], v[44:45], v[106:107]
	v_rcp_f32_e32 v40, v40
	v_rcp_f32_e32 v41, v41
	v_pk_fma_f32 v[36:37], v[242:243], v[102:103], v[36:37]
	v_pk_mul_f32 v[246:247], v[38:39], v[68:69] op_sel_hi:[1,0]
	v_pk_mul_f32 v[38:39], v[200:201], v[122:123]
	v_pk_fma_f32 v[36:37], v[206:207], v[114:115], v[36:37]
	v_pk_fma_f32 v[38:39], v[252:253], v[118:119], v[38:39]
	v_pk_add_f32 v[36:37], v[36:37], v[110:111]
	v_pk_mul_f32 v[62:63], v[62:63], v[66:67] op_sel_hi:[1,0]
	v_pk_mul_f32 v[60:61], v[60:61], v[66:67] op_sel_hi:[1,0]
	v_pk_fma_f32 v[38:39], v[210:211], v[130:131], v[38:39]
	v_mul_f32_e32 v67, 0xbfb8aa3b, v36
	v_pk_add_f32 v[38:39], v[38:39], v[126:127]
	v_pk_mul_f32 v[34:35], v[34:35], v[40:41]
	v_exp_f32_e32 v67, v67
	v_mul_f32_e32 v153, 0xbfb8aa3b, v37
	v_pk_mul_f32 v[34:35], v[34:35], v[38:39]
	v_pk_mul_f32 v[38:39], v[46:47], v[108:109]
	v_exp_f32_e32 v153, v153
	v_pk_fma_f32 v[38:39], v[244:245], v[104:105], v[38:39]
	v_pk_mul_f32 v[42:43], v[252:253], v[122:123]
	v_pk_fma_f32 v[38:39], v[204:205], v[116:117], v[38:39]
	v_pk_fma_f32 v[42:43], v[248:249], v[118:119], v[42:43]
	v_pk_add_f32 v[38:39], v[38:39], v[112:113]
	v_add_f32_e32 v67, 1.0, v67
	v_pk_mul_f32 v[40:41], v[250:251], v[124:125]
	v_pk_fma_f32 v[42:43], v[200:201], v[130:131], v[42:43]
	v_rcp_f32_e32 v200, v67
	v_add_f32_e32 v67, 1.0, v153
	v_mul_f32_e32 v153, 0xbfb8aa3b, v38
	v_pk_fma_f32 v[40:41], v[246:247], v[120:121], v[40:41]
	v_exp_f32_e32 v153, v153
	v_mul_f32_e32 v201, 0xbfb8aa3b, v39
	v_pk_fma_f32 v[40:41], v[202:203], v[132:133], v[40:41]
	v_exp_f32_e32 v203, v201
	v_rcp_f32_e32 v201, v67
	v_add_f32_e32 v67, 1.0, v153
	v_rcp_f32_e32 v202, v67
	v_add_f32_e32 v67, 1.0, v203
	v_rcp_f32_e32 v203, v67
	v_pk_add_f32 v[40:41], v[40:41], v[128:129]
	v_pk_mul_f32 v[200:201], v[36:37], v[200:201]
	v_pk_mul_f32 v[56:57], v[56:57], v[232:233] op_sel_hi:[1,0]
	v_pk_mul_f32 v[36:37], v[38:39], v[202:203]
	v_pk_add_f32 v[42:43], v[42:43], v[126:127]
	v_pk_mul_f32 v[36:37], v[36:37], v[40:41]
	v_pk_mul_f32 v[40:41], v[242:243], v[106:107]
	v_pk_mul_f32 v[58:59], v[58:59], v[232:233] op_sel_hi:[1,0]
	v_pk_fma_f32 v[40:41], v[56:57], v[102:103], v[40:41]
	v_pk_mul_f32 v[38:39], v[200:201], v[42:43]
	v_pk_fma_f32 v[40:41], v[44:45], v[114:115], v[40:41]
	v_pk_mul_f32 v[42:43], v[244:245], v[108:109]
	v_pk_add_f32 v[40:41], v[40:41], v[110:111]
	v_pk_fma_f32 v[42:43], v[58:59], v[104:105], v[42:43]
	v_mul_f32_e32 v67, 0xbfb8aa3b, v40
	v_exp_f32_e32 v67, v67
	v_pk_fma_f32 v[42:43], v[46:47], v[116:117], v[42:43]
	v_pk_mul_f32 v[44:45], v[248:249], v[122:123]
	v_pk_add_f32 v[42:43], v[42:43], v[112:113]
	v_add_f32_e32 v67, 1.0, v67
	v_mul_f32_e32 v153, 0xbfb8aa3b, v42
	v_rcp_f32_e32 v200, v67
	v_mul_f32_e32 v67, 0xbfb8aa3b, v41
	v_exp_f32_e32 v153, v153
	v_mul_f32_e32 v201, 0xbfb8aa3b, v43
	v_exp_f32_e32 v67, v67
	v_exp_f32_e32 v201, v201
	v_add_f32_e32 v153, 1.0, v153
	v_rcp_f32_e32 v202, v153
	v_add_f32_e32 v67, 1.0, v67
	v_add_f32_e32 v153, 1.0, v201
	v_rcp_f32_e32 v203, v153
	v_rcp_f32_e32 v201, v67
	v_pk_mul_f32 v[46:47], v[246:247], v[124:125]
	v_pk_fma_f32 v[44:45], v[50:51], v[118:119], v[44:45]
	v_pk_fma_f32 v[46:47], v[48:49], v[120:121], v[46:47]
	v_pk_fma_f32 v[44:45], v[252:253], v[130:131], v[44:45]
	v_pk_fma_f32 v[46:47], v[250:251], v[132:133], v[46:47]
	v_pk_add_f32 v[44:45], v[44:45], v[126:127]
	v_pk_add_f32 v[46:47], v[46:47], v[128:129]
	v_pk_mul_f32 v[42:43], v[42:43], v[202:203]
	v_pk_mul_f32 v[200:201], v[40:41], v[200:201]
	v_pk_mul_f32 v[40:41], v[42:43], v[46:47]
	v_pk_mul_f32 v[42:43], v[200:201], v[44:45]
	v_pk_mul_f32 v[44:45], v[56:57], v[106:107]
	v_pk_mul_f32 v[46:47], v[58:59], v[108:109]
	v_pk_fma_f32 v[44:45], v[60:61], v[102:103], v[44:45]
	v_pk_fma_f32 v[46:47], v[62:63], v[104:105], v[46:47]
	v_pk_fma_f32 v[44:45], v[242:243], v[114:115], v[44:45]
	v_pk_fma_f32 v[46:47], v[244:245], v[116:117], v[46:47]
	v_pk_add_f32 v[44:45], v[44:45], v[110:111]
	v_pk_add_f32 v[46:47], v[46:47], v[112:113]
	v_mul_f32_e32 v67, 0xbfb8aa3b, v44
	v_exp_f32_e32 v67, v67
	v_mul_f32_e32 v153, 0xbfb8aa3b, v46
	v_exp_f32_e32 v153, v153
	v_mul_f32_e32 v205, 0xbfb8aa3b, v47
	v_add_f32_e32 v67, 1.0, v67
	v_rcp_f32_e32 v204, v67
	v_mul_f32_e32 v67, 0xbfb8aa3b, v45
	v_exp_f32_e32 v205, v205
	v_exp_f32_e32 v67, v67
	v_add_f32_e32 v153, 1.0, v153
	v_rcp_f32_e32 v206, v153
	v_add_f32_e32 v153, 1.0, v205
	v_add_f32_e32 v67, 1.0, v67
	v_rcp_f32_e32 v207, v153
	v_pk_mul_f32 v[202:203], v[48:49], v[124:125]
	v_rcp_f32_e32 v205, v67
	v_pk_fma_f32 v[202:203], v[52:53], v[120:121], v[202:203]
	v_pk_mul_f32 v[46:47], v[46:47], v[206:207]
	v_pk_fma_f32 v[202:203], v[246:247], v[132:133], v[202:203]
	v_pk_mul_f32 v[204:205], v[44:45], v[204:205]
	v_pk_add_f32 v[202:203], v[202:203], v[128:129]
	v_pk_mul_f32 v[200:201], v[50:51], v[122:123]
	v_pk_mul_f32 v[44:45], v[46:47], v[202:203]
	v_pk_mul_f32 v[202:203], v[60:61], v[106:107]
	v_pk_fma_f32 v[200:201], v[54:55], v[118:119], v[200:201]
	v_pk_fma_f32 v[202:203], v[198:199], v[102:103], v[202:203]
	v_pk_fma_f32 v[200:201], v[248:249], v[130:131], v[200:201]
	v_pk_fma_f32 v[56:57], v[56:57], v[114:115], v[202:203]
	v_pk_add_f32 v[200:201], v[200:201], v[126:127]
	v_pk_add_f32 v[56:57], v[56:57], v[110:111]
	v_pk_mul_f32 v[46:47], v[204:205], v[200:201]
	v_mul_f32_e32 v67, 0xbfb8aa3b, v56
	v_exp_f32_e32 v67, v67
	v_pk_mul_f32 v[200:201], v[62:63], v[108:109]
	v_pk_mul_f32 v[202:203], v[54:55], v[122:123]
	v_pk_fma_f32 v[200:201], v[194:195], v[104:105], v[200:201]
	v_add_f32_e32 v67, 1.0, v67
	v_pk_fma_f32 v[58:59], v[58:59], v[116:117], v[200:201]
	v_pk_mul_f32 v[200:201], v[52:53], v[124:125]
	v_pk_add_f32 v[58:59], v[58:59], v[112:113]
	v_pk_fma_f32 v[200:201], v[196:197], v[120:121], v[200:201]
	v_mul_f32_e32 v153, 0xbfb8aa3b, v58
	v_pk_fma_f32 v[48:49], v[48:49], v[132:133], v[200:201]
	v_rcp_f32_e32 v200, v67
	v_mul_f32_e32 v67, 0xbfb8aa3b, v57
	v_exp_f32_e32 v67, v67
	v_exp_f32_e32 v153, v153
	v_mul_f32_e32 v201, 0xbfb8aa3b, v59
	v_exp_f32_e32 v201, v201
	v_pk_fma_f32 v[202:203], v[192:193], v[118:119], v[202:203]
	v_add_f32_e32 v67, 1.0, v67
	v_add_f32_e32 v153, 1.0, v153
	v_pk_fma_f32 v[50:51], v[50:51], v[130:131], v[202:203]
	v_rcp_f32_e32 v202, v153
	v_add_f32_e32 v153, 1.0, v201
	v_rcp_f32_e32 v201, v67
	v_pk_add_f32 v[50:51], v[50:51], v[126:127]
	v_rcp_f32_e32 v203, v153
	v_pk_add_f32 v[48:49], v[48:49], v[128:129]
	v_pk_mul_f32 v[56:57], v[56:57], v[200:201]
	s_andn2_b64 vcc, exec, s[6:7]
	v_pk_mul_f32 v[50:51], v[56:57], v[50:51]
	v_pk_mul_f32 v[56:57], v[194:195], v[108:109]
	v_pk_mul_f32 v[58:59], v[58:59], v[202:203]
	v_pk_fma_f32 v[56:57], v[186:187], v[104:105], v[56:57]
	v_pk_mul_f32 v[48:49], v[58:59], v[48:49]
	v_pk_fma_f32 v[56:57], v[62:63], v[116:117], v[56:57]
	v_pk_mul_f32 v[62:63], v[192:193], v[122:123]
	v_pk_add_f32 v[56:57], v[56:57], v[112:113]
	v_pk_fma_f32 v[62:63], v[184:185], v[118:119], v[62:63]
	v_pk_mul_f32 v[58:59], v[198:199], v[106:107]
	v_pk_fma_f32 v[54:55], v[54:55], v[130:131], v[62:63]
	v_mul_f32_e32 v62, 0xbfb8aa3b, v56
	v_mul_f32_e32 v63, 0xbfb8aa3b, v57
	v_exp_f32_e32 v62, v62
	v_exp_f32_e32 v63, v63
	v_pk_fma_f32 v[58:59], v[190:191], v[102:103], v[58:59]
	v_pk_add_f32 v[54:55], v[54:55], v[126:127]
	v_pk_fma_f32 v[58:59], v[60:61], v[114:115], v[58:59]
	v_pk_mul_f32 v[60:61], v[196:197], v[124:125]
	v_pk_add_f32 v[58:59], v[58:59], v[110:111]
	v_pk_fma_f32 v[60:61], v[188:189], v[120:121], v[60:61]
	v_add_f32_e32 v62, 1.0, v62
	v_add_f32_e32 v63, 1.0, v63
	v_mul_f32_e32 v67, 0xbfb8aa3b, v58
	v_pk_fma_f32 v[52:53], v[52:53], v[132:133], v[60:61]
	v_mul_f32_e32 v61, 0xbfb8aa3b, v59
	v_rcp_f32_e32 v62, v62
	v_rcp_f32_e32 v63, v63
	v_exp_f32_e32 v67, v67
	v_exp_f32_e32 v61, v61
	v_pk_add_f32 v[52:53], v[52:53], v[128:129]
	v_pk_mul_f32 v[56:57], v[56:57], v[62:63]
	v_add_f32_e32 v60, 1.0, v67
	v_add_f32_e32 v61, 1.0, v61
	v_pk_mul_f32 v[52:53], v[56:57], v[52:53]
	v_pk_mul_f32 v[56:57], v[102:103], v[226:227]
	v_rcp_f32_e32 v60, v60
	v_rcp_f32_e32 v61, v61
	v_pk_fma_f32 v[56:57], v[190:191], v[106:107], v[56:57]
	v_pk_mul_f32 v[62:63], v[118:119], v[218:219]
	v_pk_fma_f32 v[56:57], v[198:199], v[114:115], v[56:57]
	v_pk_mul_f32 v[58:59], v[58:59], v[60:61]
	v_pk_add_f32 v[56:57], v[110:111], v[56:57]
	v_pk_mul_f32 v[54:55], v[58:59], v[54:55]
	v_mul_f32_e32 v67, 0xbfb8aa3b, v56
	v_exp_f32_e32 v67, v67
	v_mul_f32_e32 v153, 0xbfb8aa3b, v57
	v_pk_mul_f32 v[58:59], v[104:105], v[230:231]
	v_exp_f32_e32 v153, v153
	v_pk_fma_f32 v[58:59], v[186:187], v[108:109], v[58:59]
	v_pk_fma_f32 v[62:63], v[184:185], v[122:123], v[62:63]
	v_pk_fma_f32 v[58:59], v[194:195], v[116:117], v[58:59]
	v_add_f32_e32 v67, 1.0, v67
	v_pk_add_f32 v[58:59], v[112:113], v[58:59]
	v_pk_fma_f32 v[62:63], v[192:193], v[130:131], v[62:63]
	v_rcp_f32_e32 v192, v67
	v_add_f32_e32 v67, 1.0, v153
	v_mul_f32_e32 v153, 0xbfb8aa3b, v58
	v_exp_f32_e32 v153, v153
	v_mul_f32_e32 v193, 0xbfb8aa3b, v59
	v_exp_f32_e32 v195, v193
	v_rcp_f32_e32 v193, v67
	v_add_f32_e32 v67, 1.0, v153
	v_rcp_f32_e32 v194, v67
	v_add_f32_e32 v67, 1.0, v195
	v_rcp_f32_e32 v195, v67
	v_pk_mul_f32 v[60:61], v[120:121], v[224:225]
	v_pk_mul_f32 v[192:193], v[56:57], v[192:193]
	v_pk_fma_f32 v[60:61], v[188:189], v[124:125], v[60:61]
	v_pk_mul_f32 v[56:57], v[58:59], v[194:195]
	v_pk_fma_f32 v[60:61], v[196:197], v[132:133], v[60:61]
	v_pk_add_f32 v[62:63], v[126:127], v[62:63]
	v_pk_add_f32 v[60:61], v[128:129], v[60:61]
	v_pk_mul_f32 v[58:59], v[62:63], v[192:193]
	v_pk_mul_f32 v[56:57], v[60:61], v[56:57]
	v_pk_mul_f32 v[60:61], v[106:107], v[226:227]
	v_pk_mul_f32 v[62:63], v[108:109], v[230:231]
	v_pk_fma_f32 v[60:61], v[102:103], v[222:223], v[60:61]
	v_pk_fma_f32 v[62:63], v[104:105], v[228:229], v[62:63]
	v_pk_fma_f32 v[60:61], v[190:191], v[114:115], v[60:61]
	v_pk_mul_f32 v[104:105], v[122:123], v[218:219]
	v_pk_add_f32 v[60:61], v[110:111], v[60:61]
	v_pk_fma_f32 v[104:105], v[118:119], v[216:217], v[104:105]
	v_mul_f32_e32 v67, 0xbfb8aa3b, v60
	v_pk_mul_f32 v[102:103], v[124:125], v[224:225]
	v_exp_f32_e32 v67, v67
	v_mul_f32_e32 v106, 0xbfb8aa3b, v61
	v_pk_fma_f32 v[104:105], v[184:185], v[130:131], v[104:105]
	v_pk_fma_f32 v[102:103], v[120:121], v[220:221], v[102:103]
	v_exp_f32_e32 v107, v106
	v_pk_add_f32 v[104:105], v[126:127], v[104:105]
	v_pk_mul_f32 v[120:121], v[14:15], v[68:69] op_sel:[0,1]
	v_pk_mul_f32 v[126:127], v[0:1], v[68:69] op_sel:[0,1]
	v_pk_mul_f32 v[0:1], v[172:173], v[76:77]
	v_pk_mul_f32 v[122:123], v[12:13], v[68:69] op_sel:[0,1]
	v_pk_mul_f32 v[124:125], v[2:3], v[68:69] op_sel:[0,1]
	v_pk_mul_f32 v[2:3], v[174:175], v[74:75]
	v_pk_fma_f32 v[0:1], v[120:121], v[72:73], v[0:1]
	v_pk_fma_f32 v[62:63], v[186:187], v[116:117], v[62:63]
	v_pk_fma_f32 v[2:3], v[122:123], v[70:71], v[2:3]
	v_pk_fma_f32 v[0:1], v[180:181], v[84:85], v[0:1]
	v_pk_add_f32 v[62:63], v[112:113], v[62:63]
	v_add_f32_e32 v67, 1.0, v67
	v_pk_fma_f32 v[2:3], v[182:183], v[82:83], v[2:3]
	v_pk_add_f32 v[0:1], v[0:1], v[80:81]
	v_rcp_f32_e32 v106, v67
	v_add_f32_e32 v67, 1.0, v107
	v_mul_f32_e32 v107, 0xbfb8aa3b, v62
	v_pk_mul_f32 v[110:111], v[26:27], v[232:233] op_sel_hi:[1,0]
	v_pk_add_f32 v[2:3], v[2:3], v[78:79]
	v_mul_f32_e32 v26, 0xbfb8aa3b, v0
	v_mul_f32_e32 v27, 0xbfb8aa3b, v1
	v_exp_f32_e32 v108, v107
	v_mul_f32_e32 v107, 0xbfb8aa3b, v63
	v_pk_mul_f32 v[112:113], v[24:25], v[232:233] op_sel_hi:[1,0]
	v_mul_f32_e32 v24, 0xbfb8aa3b, v2
	v_mul_f32_e32 v25, 0xbfb8aa3b, v3
	v_exp_f32_e32 v26, v26
	v_exp_f32_e32 v27, v27
	v_exp_f32_e32 v109, v107
	v_exp_f32_e32 v24, v24
	v_exp_f32_e32 v25, v25
	v_rcp_f32_e32 v107, v67
	v_add_f32_e32 v67, 1.0, v108
	v_add_f32_e32 v26, 1.0, v26
	v_add_f32_e32 v27, 1.0, v27
	v_rcp_f32_e32 v108, v67
	v_add_f32_e32 v67, 1.0, v109
	v_add_f32_e32 v24, 1.0, v24
	v_add_f32_e32 v25, 1.0, v25
	v_rcp_f32_e32 v26, v26
	v_rcp_f32_e32 v27, v27
	v_rcp_f32_e32 v109, v67
	v_pk_mul_f32 v[118:119], v[4:5], v[68:69] op_sel_hi:[1,0]
	v_pk_mul_f32 v[4:5], v[170:171], v[92:93]
	v_rcp_f32_e32 v24, v24
	v_rcp_f32_e32 v25, v25
	v_pk_mul_f32 v[116:117], v[6:7], v[68:69] op_sel_hi:[1,0]
	v_pk_mul_f32 v[6:7], v[168:169], v[90:91]
	v_pk_fma_f32 v[4:5], v[124:125], v[88:89], v[4:5]
	v_pk_fma_f32 v[6:7], v[126:127], v[86:87], v[6:7]
	v_pk_fma_f32 v[4:5], v[176:177], v[100:101], v[4:5]
	v_pk_mul_f32 v[106:107], v[60:61], v[106:107]
	v_pk_fma_f32 v[6:7], v[178:179], v[98:99], v[6:7]
	v_pk_add_f32 v[4:5], v[4:5], v[96:97]
	v_pk_mul_f32 v[0:1], v[0:1], v[26:27]
	v_pk_mul_f32 v[60:61], v[62:63], v[108:109]
	v_pk_mul_f32 v[62:63], v[104:105], v[106:107]
	v_pk_mul_f32 v[104:105], v[20:21], v[68:69] op_sel_hi:[1,0]
	v_pk_add_f32 v[6:7], v[6:7], v[94:95]
	v_pk_mul_f32 v[2:3], v[2:3], v[24:25]
	v_pk_mul_f32 v[0:1], v[0:1], v[4:5]
	v_pk_mul_f32 v[4:5], v[122:123], v[74:75]
	v_pk_mul_f32 v[114:115], v[22:23], v[68:69] op_sel_hi:[1,0]
	v_pk_mul_f32 v[2:3], v[2:3], v[6:7]
	v_pk_mul_f32 v[6:7], v[120:121], v[76:77]
	v_pk_fma_f32 v[4:5], v[104:105], v[70:71], v[4:5]
	v_pk_fma_f32 v[102:103], v[188:189], v[132:133], v[102:103]
	v_pk_fma_f32 v[6:7], v[114:115], v[72:73], v[6:7]
	v_pk_fma_f32 v[4:5], v[174:175], v[82:83], v[4:5]
	v_pk_add_f32 v[102:103], v[128:129], v[102:103]
	v_pk_fma_f32 v[6:7], v[172:173], v[84:85], v[6:7]
	v_pk_add_f32 v[4:5], v[4:5], v[78:79]
	v_pk_mul_f32 v[60:61], v[102:103], v[60:61]
	v_pk_mul_f32 v[68:69], v[30:31], v[66:67] op_sel_hi:[1,0]
	v_pk_mul_f32 v[102:103], v[28:29], v[66:67] op_sel_hi:[1,0]
	v_pk_mul_f32 v[28:29], v[18:19], v[66:67] op_sel_hi:[1,0]
	v_pk_mul_f32 v[30:31], v[16:17], v[66:67] op_sel_hi:[1,0]
	v_pk_add_f32 v[6:7], v[6:7], v[80:81]
	v_mul_f32_e32 v66, 0xbfb8aa3b, v4
	v_mul_f32_e32 v67, 0xbfb8aa3b, v5
	v_exp_f32_e32 v66, v66
	v_exp_f32_e32 v67, v67
	v_mul_f32_e32 v128, 0xbfb8aa3b, v6
	v_mul_f32_e32 v129, 0xbfb8aa3b, v7
	v_exp_f32_e32 v128, v128
	v_exp_f32_e32 v129, v129
	v_add_f32_e32 v66, 1.0, v66
	v_add_f32_e32 v67, 1.0, v67
	v_rcp_f32_e32 v66, v66
	v_rcp_f32_e32 v67, v67
	v_add_f32_e32 v128, 1.0, v128
	v_add_f32_e32 v129, 1.0, v129
	v_pk_mul_f32 v[26:27], v[126:127], v[90:91]
	v_rcp_f32_e32 v128, v128
	v_rcp_f32_e32 v129, v129
	v_pk_mul_f32 v[24:25], v[124:125], v[92:93]
	v_pk_fma_f32 v[26:27], v[118:119], v[86:87], v[26:27]
	v_pk_fma_f32 v[24:25], v[116:117], v[88:89], v[24:25]
	v_pk_fma_f32 v[26:27], v[168:169], v[98:99], v[26:27]
	v_pk_fma_f32 v[24:25], v[170:171], v[100:101], v[24:25]
	v_pk_add_f32 v[26:27], v[26:27], v[94:95]
	v_pk_mul_f32 v[66:67], v[4:5], v[66:67]
	v_pk_add_f32 v[24:25], v[24:25], v[96:97]
	v_pk_mul_f32 v[4:5], v[6:7], v[128:129]
	v_pk_mul_f32 v[6:7], v[66:67], v[26:27]
	v_pk_mul_f32 v[26:27], v[114:115], v[76:77]
	v_pk_mul_f32 v[4:5], v[4:5], v[24:25]
	v_pk_mul_f32 v[24:25], v[104:105], v[74:75]
	v_pk_fma_f32 v[26:27], v[110:111], v[72:73], v[26:27]
	v_pk_mul_f32 v[106:107], v[10:11], v[232:233] op_sel_hi:[1,0]
	v_pk_fma_f32 v[24:25], v[112:113], v[70:71], v[24:25]
	v_pk_fma_f32 v[26:27], v[120:121], v[84:85], v[26:27]
	v_pk_mul_f32 v[120:121], v[116:117], v[92:93]
	v_pk_fma_f32 v[24:25], v[122:123], v[82:83], v[24:25]
	v_pk_add_f32 v[26:27], v[26:27], v[80:81]
	v_pk_fma_f32 v[120:121], v[106:107], v[88:89], v[120:121]
	v_pk_add_f32 v[24:25], v[24:25], v[78:79]
	v_pk_fma_f32 v[120:121], v[124:125], v[100:101], v[120:121]
	v_mul_f32_e32 v124, 0xbfb8aa3b, v26
	v_mul_f32_e32 v125, 0xbfb8aa3b, v27
	v_mul_f32_e32 v122, 0xbfb8aa3b, v24
	v_mul_f32_e32 v123, 0xbfb8aa3b, v25
	v_exp_f32_e32 v124, v124
	v_exp_f32_e32 v125, v125
	v_exp_f32_e32 v122, v122
	v_exp_f32_e32 v123, v123
	v_add_f32_e32 v124, 1.0, v124
	v_add_f32_e32 v125, 1.0, v125
	v_add_f32_e32 v122, 1.0, v122
	v_add_f32_e32 v123, 1.0, v123
	v_rcp_f32_e32 v124, v124
	v_rcp_f32_e32 v125, v125
	v_rcp_f32_e32 v122, v122
	v_rcp_f32_e32 v123, v123
	v_pk_mul_f32 v[108:109], v[8:9], v[232:233] op_sel_hi:[1,0]
	v_pk_mul_f32 v[66:67], v[118:119], v[90:91]
	v_pk_add_f32 v[120:121], v[120:121], v[96:97]
	v_pk_fma_f32 v[66:67], v[108:109], v[86:87], v[66:67]
	v_pk_mul_f32 v[26:27], v[26:27], v[124:125]
	v_pk_fma_f32 v[66:67], v[126:127], v[98:99], v[66:67]
	v_pk_mul_f32 v[122:123], v[24:25], v[122:123]
	v_pk_add_f32 v[66:67], v[66:67], v[94:95]
	v_pk_mul_f32 v[24:25], v[26:27], v[120:121]
	v_pk_mul_f32 v[120:121], v[110:111], v[76:77]
	v_pk_mul_f32 v[26:27], v[122:123], v[66:67]
	v_pk_mul_f32 v[66:67], v[112:113], v[74:75]
	v_pk_fma_f32 v[120:121], v[68:69], v[72:73], v[120:121]
	v_pk_fma_f32 v[66:67], v[102:103], v[70:71], v[66:67]
	v_pk_fma_f32 v[114:115], v[114:115], v[84:85], v[120:121]
	v_pk_fma_f32 v[66:67], v[104:105], v[82:83], v[66:67]
	v_pk_add_f32 v[104:105], v[114:115], v[80:81]
	v_pk_mul_f32 v[114:115], v[108:109], v[90:91]
	v_pk_mul_f32 v[120:121], v[106:107], v[92:93]
	v_pk_add_f32 v[66:67], v[66:67], v[78:79]
	v_pk_fma_f32 v[120:121], v[28:29], v[88:89], v[120:121]
	v_pk_fma_f32 v[114:115], v[30:31], v[86:87], v[114:115]
	v_mul_f32_e32 v122, 0xbfb8aa3b, v66
	v_pk_fma_f32 v[116:117], v[116:117], v[100:101], v[120:121]
	v_pk_fma_f32 v[114:115], v[118:119], v[98:99], v[114:115]
	v_mul_f32_e32 v119, 0xbfb8aa3b, v67
	v_mul_f32_e32 v120, 0xbfb8aa3b, v104
	v_mul_f32_e32 v121, 0xbfb8aa3b, v105
	v_exp_f32_e32 v122, v122
	v_exp_f32_e32 v119, v119
	v_exp_f32_e32 v120, v120
	v_exp_f32_e32 v121, v121
	v_add_f32_e32 v118, 1.0, v122
	v_add_f32_e32 v119, 1.0, v119
	v_add_f32_e32 v120, 1.0, v120
	v_add_f32_e32 v121, 1.0, v121
	v_rcp_f32_e32 v118, v118
	v_rcp_f32_e32 v120, v120
	v_rcp_f32_e32 v121, v121
	v_rcp_f32_e32 v119, v119
	v_pk_add_f32 v[116:117], v[116:117], v[96:97]
	v_pk_add_f32 v[114:115], v[114:115], v[94:95]
	v_pk_mul_f32 v[104:105], v[104:105], v[120:121]
	v_pk_mul_f32 v[118:119], v[66:67], v[118:119]
	v_pk_mul_f32 v[66:67], v[104:105], v[116:117]
	v_pk_mul_f32 v[104:105], v[118:119], v[114:115]
	v_pk_mul_f32 v[114:115], v[68:69], v[76:77]
	v_pk_mul_f32 v[116:117], v[102:103], v[74:75]
	v_pk_fma_f32 v[114:115], v[162:163], v[72:73], v[114:115]
	v_pk_fma_f32 v[116:117], v[166:167], v[70:71], v[116:117]
	v_pk_fma_f32 v[110:111], v[110:111], v[84:85], v[114:115]
	v_pk_fma_f32 v[112:113], v[112:113], v[82:83], v[116:117]
	v_pk_mul_f32 v[114:115], v[28:29], v[92:93]
	v_pk_mul_f32 v[116:117], v[30:31], v[90:91]
	v_pk_add_f32 v[110:111], v[110:111], v[80:81]
	v_pk_add_f32 v[112:113], v[112:113], v[78:79]
	v_pk_fma_f32 v[116:117], v[64:65], v[86:87], v[116:117]
	v_pk_fma_f32 v[114:115], v[164:165], v[88:89], v[114:115]
	v_mul_f32_e32 v118, 0xbfb8aa3b, v112
	v_pk_fma_f32 v[106:107], v[106:107], v[100:101], v[114:115]
	v_pk_fma_f32 v[108:109], v[108:109], v[98:99], v[116:117]
	v_mul_f32_e32 v115, 0xbfb8aa3b, v113
	v_mul_f32_e32 v116, 0xbfb8aa3b, v110
	v_mul_f32_e32 v117, 0xbfb8aa3b, v111
	v_exp_f32_e32 v118, v118
	v_exp_f32_e32 v115, v115
	v_exp_f32_e32 v116, v116
	v_exp_f32_e32 v117, v117
	v_add_f32_e32 v114, 1.0, v118
	v_add_f32_e32 v115, 1.0, v115
	v_add_f32_e32 v116, 1.0, v116
	v_add_f32_e32 v117, 1.0, v117
	v_rcp_f32_e32 v114, v114
	v_rcp_f32_e32 v116, v116
	v_rcp_f32_e32 v117, v117
	v_rcp_f32_e32 v115, v115
	v_pk_add_f32 v[106:107], v[106:107], v[96:97]
	v_pk_add_f32 v[108:109], v[108:109], v[94:95]
	v_pk_mul_f32 v[110:111], v[110:111], v[116:117]
	v_pk_mul_f32 v[112:113], v[112:113], v[114:115]
	v_pk_mul_f32 v[106:107], v[110:111], v[106:107]
	v_pk_mul_f32 v[108:109], v[112:113], v[108:109]
	v_pk_mul_f32 v[110:111], v[162:163], v[76:77]
	v_pk_mul_f32 v[112:113], v[166:167], v[74:75]
	v_pk_fma_f32 v[110:111], v[156:157], v[72:73], v[110:111]
	v_pk_fma_f32 v[112:113], v[160:161], v[70:71], v[112:113]
	v_pk_fma_f32 v[68:69], v[68:69], v[84:85], v[110:111]
	v_pk_fma_f32 v[102:103], v[102:103], v[82:83], v[112:113]
	v_pk_mul_f32 v[110:111], v[164:165], v[92:93]
	v_pk_mul_f32 v[112:113], v[64:65], v[90:91]
	v_pk_add_f32 v[68:69], v[68:69], v[80:81]
	v_pk_add_f32 v[102:103], v[102:103], v[78:79]
	v_pk_fma_f32 v[112:113], v[134:135], v[86:87], v[112:113]
	v_pk_fma_f32 v[110:111], v[158:159], v[88:89], v[110:111]
	v_mul_f32_e32 v114, 0xbfb8aa3b, v102
	v_pk_fma_f32 v[28:29], v[28:29], v[100:101], v[110:111]
	v_pk_fma_f32 v[30:31], v[30:31], v[98:99], v[112:113]
	v_mul_f32_e32 v111, 0xbfb8aa3b, v103
	v_mul_f32_e32 v112, 0xbfb8aa3b, v68
	v_mul_f32_e32 v113, 0xbfb8aa3b, v69
	v_exp_f32_e32 v114, v114
	v_exp_f32_e32 v111, v111
	v_exp_f32_e32 v112, v112
	v_exp_f32_e32 v113, v113
	v_add_f32_e32 v110, 1.0, v114
	v_add_f32_e32 v111, 1.0, v111
	v_add_f32_e32 v112, 1.0, v112
	v_add_f32_e32 v113, 1.0, v113
	v_rcp_f32_e32 v110, v110
	v_rcp_f32_e32 v112, v112
	v_rcp_f32_e32 v113, v113
	v_rcp_f32_e32 v111, v111
	v_mov_b32_dpp v18, v182 row_shr:1 row_mask:0xf bank_mask:0xf bound_ctrl:1
	v_mov_b32_dpp v19, v183 row_shr:1 row_mask:0xf bank_mask:0xf bound_ctrl:1
	v_mov_b32_dpp v22, v180 row_shr:1 row_mask:0xf bank_mask:0xf bound_ctrl:1
	v_mov_b32_dpp v23, v181 row_shr:1 row_mask:0xf bank_mask:0xf bound_ctrl:1
	v_pk_add_f32 v[28:29], v[28:29], v[96:97]
	v_pk_add_f32 v[30:31], v[30:31], v[94:95]
	v_pk_mul_f32 v[68:69], v[68:69], v[112:113]
	v_pk_mul_f32 v[102:103], v[102:103], v[110:111]
	v_mov_b32_dpp v14, v174 row_shr:1 row_mask:0xf bank_mask:0xf bound_ctrl:1
	v_mov_b32_dpp v15, v175 row_shr:1 row_mask:0xf bank_mask:0xf bound_ctrl:1
	v_mov_b32_dpp v20, v172 row_shr:1 row_mask:0xf bank_mask:0xf bound_ctrl:1
	v_mov_b32_dpp v21, v173 row_shr:1 row_mask:0xf bank_mask:0xf bound_ctrl:1
	v_pk_mul_f32 v[28:29], v[68:69], v[28:29]
	v_pk_mul_f32 v[30:31], v[102:103], v[30:31]
	v_pk_mul_f32 v[68:69], v[70:71], v[18:19]
	v_pk_mul_f32 v[102:103], v[72:73], v[22:23]
	v_pk_mul_f32 v[18:19], v[74:75], v[18:19]
	v_pk_mul_f32 v[22:23], v[76:77], v[22:23]
	v_pk_fma_f32 v[14:15], v[70:71], v[14:15], v[18:19]
	v_pk_fma_f32 v[20:21], v[72:73], v[20:21], v[22:23]
	v_mov_b32_dpp v10, v178 row_shr:1 row_mask:0xf bank_mask:0xf bound_ctrl:1
	v_mov_b32_dpp v11, v179 row_shr:1 row_mask:0xf bank_mask:0xf bound_ctrl:1
	v_mov_b32_dpp v16, v176 row_shr:1 row_mask:0xf bank_mask:0xf bound_ctrl:1
	v_mov_b32_dpp v17, v177 row_shr:1 row_mask:0xf bank_mask:0xf bound_ctrl:1
	v_pk_fma_f32 v[68:69], v[160:161], v[74:75], v[68:69]
	v_pk_fma_f32 v[14:15], v[160:161], v[82:83], v[14:15]
	v_pk_fma_f32 v[18:19], v[156:157], v[84:85], v[20:21]
	v_mov_b32_dpp v8, v168 row_shr:1 row_mask:0xf bank_mask:0xf bound_ctrl:1
	v_mov_b32_dpp v9, v169 row_shr:1 row_mask:0xf bank_mask:0xf bound_ctrl:1
	v_mov_b32_dpp v12, v170 row_shr:1 row_mask:0xf bank_mask:0xf bound_ctrl:1
	v_mov_b32_dpp v13, v171 row_shr:1 row_mask:0xf bank_mask:0xf bound_ctrl:1
	v_pk_fma_f32 v[68:69], v[166:167], v[82:83], v[68:69]
	v_pk_mul_f32 v[110:111], v[88:89], v[16:17]
	v_pk_mul_f32 v[112:113], v[86:87], v[10:11]
	v_pk_add_f32 v[18:19], v[80:81], v[18:19]
	v_pk_add_f32 v[14:15], v[78:79], v[14:15]
	v_pk_mul_f32 v[16:17], v[92:93], v[16:17]
	v_pk_mul_f32 v[10:11], v[90:91], v[10:11]
	v_pk_add_f32 v[68:69], v[78:79], v[68:69]
	v_pk_fma_f32 v[8:9], v[86:87], v[8:9], v[10:11]
	v_pk_fma_f32 v[10:11], v[88:89], v[12:13], v[16:17]
	v_mul_f32_e32 v12, 0xbfb8aa3b, v14
	v_mul_f32_e32 v13, 0xbfb8aa3b, v15
	v_mul_f32_e32 v16, 0xbfb8aa3b, v18
	v_mul_f32_e32 v17, 0xbfb8aa3b, v19
	v_mul_f32_e32 v114, 0xbfb8aa3b, v68
	v_mul_f32_e32 v115, 0xbfb8aa3b, v69
	v_exp_f32_e32 v12, v12
	v_exp_f32_e32 v13, v13
	v_exp_f32_e32 v16, v16
	v_exp_f32_e32 v17, v17
	v_exp_f32_e32 v114, v114
	v_exp_f32_e32 v115, v115
	v_pk_fma_f32 v[102:103], v[156:157], v[76:77], v[102:103]
	v_pk_fma_f32 v[112:113], v[134:135], v[90:91], v[112:113]
	v_pk_fma_f32 v[102:103], v[162:163], v[84:85], v[102:103]
	v_add_f32_e32 v12, 1.0, v12
	v_pk_add_f32 v[102:103], v[80:81], v[102:103]
	v_add_f32_e32 v13, 1.0, v13
	v_add_f32_e32 v16, 1.0, v16
	v_add_f32_e32 v17, 1.0, v17
	v_pk_fma_f32 v[64:65], v[64:65], v[98:99], v[112:113]
	v_add_f32_e32 v112, 1.0, v114
	v_add_f32_e32 v113, 1.0, v115
	v_mul_f32_e32 v114, 0xbfb8aa3b, v102
	v_mul_f32_e32 v115, 0xbfb8aa3b, v103
	v_rcp_f32_e32 v12, v12
	v_rcp_f32_e32 v13, v13
	v_rcp_f32_e32 v16, v16
	v_rcp_f32_e32 v17, v17
	v_exp_f32_e32 v114, v114
	v_exp_f32_e32 v115, v115
	v_pk_fma_f32 v[10:11], v[158:159], v[100:101], v[10:11]
	v_pk_fma_f32 v[8:9], v[134:135], v[98:99], v[8:9]
	v_pk_add_f32 v[10:11], v[96:97], v[10:11]
	v_pk_add_f32 v[8:9], v[94:95], v[8:9]
	v_pk_mul_f32 v[12:13], v[14:15], v[12:13]
	v_pk_mul_f32 v[14:15], v[18:19], v[16:17]
	v_add_f32_e32 v114, 1.0, v114
	v_add_f32_e32 v115, 1.0, v115
	v_pk_mul_f32 v[14:15], v[10:11], v[14:15]
	v_pk_mul_f32 v[10:11], v[8:9], v[12:13]
	v_mov_b64_e32 v[12:13], s[16:17]
	v_readfirstlane_b32 s62, v152
	v_readfirstlane_b32 s63, v154
	v_mbcnt_lo_u32_b32 v176, -1, 0
	v_mbcnt_hi_u32_b32 v176, -1, v176
	v_lshrrev_b32_e32 v177, 2, v176
	v_and_b32_e32 v178, 3, v176
	s_mul_i32 s62, s62, 0x1600
	s_lshl_b32 s63, s63, 1
	s_add_i32 s62, s62, s63
	v_mul_u32_u24_e32 v179, 0xb000, v177
	v_lshl_add_u32 v179, v178, 4, v179
	v_add_u32_e32 v179, s62, v179
	s_lshr_b32 s63, s33, 6
	s_mulk_i32 s63, 0x500
	s_add_i32 s63, s63, 0x20400
	v_mul_u32_u24_e32 v188, 0x50, v177
	v_lshl_add_u32 v188, v178, 4, v188
	v_add_u32_e32 v188, s63, v188
	v_and_b32_e32 v177, 15, v176
	v_lshrrev_b32_e32 v178, 4, v176
	v_mul_u32_u24_e32 v189, 0x50, v177
	v_lshl_add_u32 v189, v178, 4, v189
	v_add_u32_e32 v189, s63, v189
	v_rcp_f32_e32 v112, v112
	v_rcp_f32_e32 v113, v113
	v_rcp_f32_e32 v114, v114
	v_rcp_f32_e32 v115, v115
	v_cvt_pk_bf16_f32 v8, v62, v63
	v_cvt_pk_bf16_f32 v9, v60, v61
	v_cvt_pk_bf16_f32 v10, v10, v11
	v_cvt_pk_bf16_f32 v11, v14, v15
	v_mad_i64_i32 v[14:15], s[26:27], v152, s93, v[12:13]
	v_lshlrev_b64 v[16:17], 1, v[154:155]
	v_lshl_add_u64 v[14:15], v[14:15], 0, v[16:17]
	v_pk_fma_f32 v[110:111], v[158:159], v[92:93], v[110:111]
	ds_write_b128 v189, v[8:11]
	ds_read_b128 v[180:183], v188
	s_waitcnt lgkmcnt(0)
	global_store_dwordx4 v179, v[180:183], s[16:17]
	v_or_b32_e32 v14, 1, v152
	v_pk_fma_f32 v[110:111], v[164:165], v[100:101], v[110:111]
	v_mad_i64_i32 v[14:15], s[26:27], v14, s93, v[12:13]
	v_pk_add_f32 v[64:65], v[94:95], v[64:65]
	v_pk_add_f32 v[110:111], v[96:97], v[110:111]
	v_pk_mul_f32 v[68:69], v[68:69], v[112:113]
	v_pk_mul_f32 v[102:103], v[102:103], v[114:115]
	v_lshl_add_u64 v[14:15], v[14:15], 0, v[16:17]
	v_pk_mul_f32 v[102:103], v[110:111], v[102:103]
	v_pk_mul_f32 v[64:65], v[64:65], v[68:69]
	v_cvt_pk_bf16_f32 v8, v58, v59
	v_cvt_pk_bf16_f32 v9, v56, v57
	s_mov_b64 s[6:7], -1
	v_cvt_pk_bf16_f32 v10, v64, v65
	v_cvt_pk_bf16_f32 v11, v102, v103
	ds_write_b128 v189, v[8:11]
	ds_read_b128 v[184:187], v188
	v_add_u32_e32 v190, 0x1600, v179
	s_waitcnt lgkmcnt(0)
	global_store_dwordx4 v190, v[184:187], s[16:17]
	v_or_b32_e32 v14, 2, v152
	v_mad_i64_i32 v[14:15], s[26:27], v14, s93, v[12:13]
	v_lshl_add_u64 v[14:15], v[14:15], 0, v[16:17]
	v_cvt_pk_bf16_f32 v8, v54, v55
	v_cvt_pk_bf16_f32 v9, v52, v53
	v_cvt_pk_bf16_f32 v10, v30, v31
	v_cvt_pk_bf16_f32 v11, v28, v29
	ds_write_b128 v189, v[8:11]
	ds_read_b128 v[180:183], v188
	v_add_u32_e32 v190, 0x2c00, v179
	s_waitcnt lgkmcnt(0)
	global_store_dwordx4 v190, v[180:183], s[16:17]
	v_or_b32_e32 v14, 3, v152
	v_mad_i64_i32 v[14:15], s[26:27], v14, s93, v[12:13]
	v_lshl_add_u64 v[14:15], v[14:15], 0, v[16:17]
	v_cvt_pk_bf16_f32 v8, v50, v51
	v_cvt_pk_bf16_f32 v9, v48, v49
	v_cvt_pk_bf16_f32 v10, v108, v109
	v_cvt_pk_bf16_f32 v11, v106, v107
	ds_write_b128 v189, v[8:11]
	ds_read_b128 v[184:187], v188
	v_add_u32_e32 v190, 0x4200, v179
	s_waitcnt lgkmcnt(0)
	global_store_dwordx4 v190, v[184:187], s[16:17]
	v_or_b32_e32 v14, 4, v152
	v_mad_i64_i32 v[14:15], s[26:27], v14, s93, v[12:13]
	v_lshl_add_u64 v[14:15], v[14:15], 0, v[16:17]
	v_cvt_pk_bf16_f32 v8, v46, v47
	v_cvt_pk_bf16_f32 v9, v44, v45
	v_cvt_pk_bf16_f32 v10, v104, v105
	v_cvt_pk_bf16_f32 v11, v66, v67
	ds_write_b128 v189, v[8:11]
	ds_read_b128 v[180:183], v188
	v_add_u32_e32 v190, 0x5800, v179
	s_waitcnt lgkmcnt(0)
	global_store_dwordx4 v190, v[180:183], s[16:17]
	v_or_b32_e32 v14, 5, v152
	v_mad_i64_i32 v[14:15], s[26:27], v14, s93, v[12:13]
	v_cvt_pk_bf16_f32 v8, v42, v43
	v_cvt_pk_bf16_f32 v9, v40, v41
	v_cvt_pk_bf16_f32 v10, v26, v27
	v_cvt_pk_bf16_f32 v11, v24, v25
	v_lshl_add_u64 v[14:15], v[14:15], 0, v[16:17]
	ds_write_b128 v189, v[8:11]
	ds_read_b128 v[184:187], v188
	v_add_u32_e32 v190, 0x6e00, v179
	s_waitcnt lgkmcnt(0)
	global_store_dwordx4 v190, v[184:187], s[16:17]
	s_nop 1
	v_cvt_pk_bf16_f32 v8, v38, v39
	v_cvt_pk_bf16_f32 v9, v36, v37
	v_cvt_pk_bf16_f32 v10, v6, v7
	v_cvt_pk_bf16_f32 v11, v4, v5
	v_or_b32_e32 v4, 6, v152
	v_mad_i64_i32 v[4:5], s[26:27], v4, s93, v[12:13]
	v_lshl_add_u64 v[4:5], v[4:5], 0, v[16:17]
	ds_write_b128 v189, v[8:11]
	ds_read_b128 v[180:183], v188
	v_add_u32_e32 v190, 0x8400, v179
	s_waitcnt lgkmcnt(0)
	global_store_dwordx4 v190, v[180:183], s[16:17]
	v_cvt_pk_bf16_f32 v4, v34, v35
	v_cvt_pk_bf16_f32 v5, v32, v33
	v_cvt_pk_bf16_f32 v6, v2, v3
	v_cvt_pk_bf16_f32 v7, v0, v1
	v_or_b32_e32 v0, 7, v152
	v_mad_i64_i32 v[0:1], s[26:27], v0, s93, v[12:13]
	v_lshl_add_u64 v[0:1], v[0:1], 0, v[16:17]
	ds_write_b128 v189, v[4:7]
	ds_read_b128 v[184:187], v188
	v_add_u32_e32 v190, 0x9a00, v179
	s_waitcnt lgkmcnt(0)
	global_store_dwordx4 v190, v[184:187], s[16:17]
	s_cbranch_vccnz .LBB0_878
	s_andn2_b64 vcc, exec, s[0:1]
	s_cbranch_vccnz .LBB0_877
	s_barrier
	s_branch .LBB0_877
